# phase0 GEMV loop unrolled with three iterations of weight rows in flight (48 loads)
# baseline (speedup 1.0000x reference)
; __device__ __forceinline__ void phase0(int wv, const Params& p, LAS unsigned char* lds, int cb_first, int cb_stride, int cb_lo, int cb_hi, bool do_rope) {
;     ...
;         const int l = cb / 96, nb = cb % 96, nl = tid & 63, ks = tid >> 6;
;         const float* w = p.ada_w + ((size_t)l * 1024 + ks * 128) * 6144 + nb * 64 + nl;
;         float acc[9];
; #pragma unroll
;         for (int i = 0; i < 9; ++i) acc[i] = 0.f;
;         for (int k0 = 0; k0 < 128; k0 += 16) { float wq[16];
; #pragma unroll
;             for (int u = 0; u < 16; ++u) wq[u] = w[(size_t)(k0 + u) * 6144];
.LBB0_18:
	s_or_b64 exec, exec, s[40:41]
	s_mul_hi_i32 s16, s52, 0x2aaaaaab
	s_lshr_b32 s17, s16, 31
	s_ashr_i32 s16, s16, 4
	s_add_i32 s20, s16, s17
	s_mul_i32 s16, s20, 0x60
	s_ashr_i32 s21, s20, 31
	s_sub_i32 s18, s52, s16
	s_lshl_b64 s[16:17], s[20:21], 10
	v_lshl_add_u64 v[0:1], s[16:17], 0, v[120:121]
	v_mov_b64_e32 v[2:3], s[26:27]
	v_mad_u64_u32 v[2:3], s[16:17], v0, s51, v[2:3]
	s_lshl_b32 s40, s18, 6
	v_mad_i32_i24 v3, v1, s51, v3
	s_ashr_i32 s41, s40, 31
	v_lshl_add_u64 v[0:1], s[40:41], 2, v[2:3]
	v_mov_b32_e32 v127, v123
	v_mov_b32_e32 v130, 0
	v_lshl_add_u64 v[128:129], v[0:1], 0, v[126:127]
	s_mov_b32 s21, -16
	v_mov_b32_e32 v122, v119
	v_mov_b32_e32 v131, v130
	v_mov_b32_e32 v132, v130
	v_mov_b32_e32 v133, v130
	v_mov_b32_e32 v134, v130
	v_mov_b32_e32 v135, v130
	v_mov_b32_e32 v136, v130
	v_mov_b32_e32 v137, v130
	v_mov_b32_e32 v127, v130
	s_waitcnt lgkmcnt(0)
	s_barrier
	s_mov_b32 s18, 0x6000
	s_mov_b32 s19, 0
	global_load_dword v0, v[128:129], off
	v_lshl_add_u64 v[128:129], v[128:129], 0, s[18:19]
	global_load_dword v1, v[128:129], off
	v_lshl_add_u64 v[128:129], v[128:129], 0, s[18:19]
	global_load_dword v2, v[128:129], off
	v_lshl_add_u64 v[128:129], v[128:129], 0, s[18:19]
	global_load_dword v3, v[128:129], off
	v_lshl_add_u64 v[128:129], v[128:129], 0, s[18:19]
	global_load_dword v4, v[128:129], off
	v_lshl_add_u64 v[128:129], v[128:129], 0, s[18:19]
	global_load_dword v5, v[128:129], off
	v_lshl_add_u64 v[128:129], v[128:129], 0, s[18:19]
	global_load_dword v6, v[128:129], off
	v_lshl_add_u64 v[128:129], v[128:129], 0, s[18:19]
	global_load_dword v7, v[128:129], off
	v_lshl_add_u64 v[128:129], v[128:129], 0, s[18:19]
	global_load_dword v8, v[128:129], off
	v_lshl_add_u64 v[128:129], v[128:129], 0, s[18:19]
	global_load_dword v9, v[128:129], off
	v_lshl_add_u64 v[128:129], v[128:129], 0, s[18:19]
	global_load_dword v10, v[128:129], off
	v_lshl_add_u64 v[128:129], v[128:129], 0, s[18:19]
	global_load_dword v11, v[128:129], off
	v_lshl_add_u64 v[128:129], v[128:129], 0, s[18:19]
	global_load_dword v12, v[128:129], off
	v_lshl_add_u64 v[128:129], v[128:129], 0, s[18:19]
	global_load_dword v13, v[128:129], off
	v_lshl_add_u64 v[128:129], v[128:129], 0, s[18:19]
	global_load_dword v14, v[128:129], off
	v_lshl_add_u64 v[128:129], v[128:129], 0, s[18:19]
	global_load_dword v15, v[128:129], off
	v_lshl_add_u64 v[128:129], v[128:129], 0, s[18:19]
	global_load_dword v16, v[128:129], off
	v_lshl_add_u64 v[128:129], v[128:129], 0, s[18:19]
	global_load_dword v17, v[128:129], off
	v_lshl_add_u64 v[128:129], v[128:129], 0, s[18:19]
	global_load_dword v18, v[128:129], off
	v_lshl_add_u64 v[128:129], v[128:129], 0, s[18:19]
	global_load_dword v19, v[128:129], off
	v_lshl_add_u64 v[128:129], v[128:129], 0, s[18:19]
	global_load_dword v20, v[128:129], off
	v_lshl_add_u64 v[128:129], v[128:129], 0, s[18:19]
	global_load_dword v21, v[128:129], off
	v_lshl_add_u64 v[128:129], v[128:129], 0, s[18:19]
	global_load_dword v22, v[128:129], off
	v_lshl_add_u64 v[128:129], v[128:129], 0, s[18:19]
	global_load_dword v23, v[128:129], off
	v_lshl_add_u64 v[128:129], v[128:129], 0, s[18:19]
	global_load_dword v24, v[128:129], off
	v_lshl_add_u64 v[128:129], v[128:129], 0, s[18:19]
	global_load_dword v25, v[128:129], off
	v_lshl_add_u64 v[128:129], v[128:129], 0, s[18:19]
	global_load_dword v26, v[128:129], off
	v_lshl_add_u64 v[128:129], v[128:129], 0, s[18:19]
	global_load_dword v27, v[128:129], off
	v_lshl_add_u64 v[128:129], v[128:129], 0, s[18:19]
	global_load_dword v28, v[128:129], off
	v_lshl_add_u64 v[128:129], v[128:129], 0, s[18:19]
	global_load_dword v29, v[128:129], off
	v_lshl_add_u64 v[128:129], v[128:129], 0, s[18:19]
	global_load_dword v30, v[128:129], off
	v_lshl_add_u64 v[128:129], v[128:129], 0, s[18:19]
	global_load_dword v31, v[128:129], off
	v_lshl_add_u64 v[128:129], v[128:129], 0, s[18:19]
	global_load_dword v146, v[128:129], off
	v_lshl_add_u64 v[128:129], v[128:129], 0, s[18:19]
	global_load_dword v147, v[128:129], off
	v_lshl_add_u64 v[128:129], v[128:129], 0, s[18:19]
	global_load_dword v148, v[128:129], off
	v_lshl_add_u64 v[128:129], v[128:129], 0, s[18:19]
	global_load_dword v149, v[128:129], off
	v_lshl_add_u64 v[128:129], v[128:129], 0, s[18:19]
	global_load_dword v150, v[128:129], off
	v_lshl_add_u64 v[128:129], v[128:129], 0, s[18:19]
	global_load_dword v151, v[128:129], off
	v_lshl_add_u64 v[128:129], v[128:129], 0, s[18:19]
	global_load_dword v152, v[128:129], off
	v_lshl_add_u64 v[128:129], v[128:129], 0, s[18:19]
	global_load_dword v153, v[128:129], off
	v_lshl_add_u64 v[128:129], v[128:129], 0, s[18:19]
	global_load_dword v154, v[128:129], off
	v_lshl_add_u64 v[128:129], v[128:129], 0, s[18:19]
	global_load_dword v155, v[128:129], off
	v_lshl_add_u64 v[128:129], v[128:129], 0, s[18:19]
	global_load_dword v156, v[128:129], off
	v_lshl_add_u64 v[128:129], v[128:129], 0, s[18:19]
	global_load_dword v157, v[128:129], off
	v_lshl_add_u64 v[128:129], v[128:129], 0, s[18:19]
	global_load_dword v158, v[128:129], off
	v_lshl_add_u64 v[128:129], v[128:129], 0, s[18:19]
	global_load_dword v159, v[128:129], off
	v_lshl_add_u64 v[128:129], v[128:129], 0, s[18:19]
	global_load_dword v160, v[128:129], off
	v_lshl_add_u64 v[128:129], v[128:129], 0, s[18:19]
	global_load_dword v161, v[128:129], off
	v_lshl_add_u64 v[128:129], v[128:129], 0, s[18:19]
; __device__ __forceinline__ void phase0(int wv, const Params& p, LAS unsigned char* lds, int cb_first, int cb_stride, int cb_lo, int cb_hi, bool do_rope) {
;     ...
;         for (int k0 = 0; k0 < 128; k0 += 16) { float wq[16];
; #pragma unroll
;             for (int u = 0; u < 16; ++u) wq[u] = w[(size_t)(k0 + u) * 6144];
; #pragma unroll
;             for (int u = 0; u < 16; ++u)
; #pragma unroll
;                 for (int i = 0; i < 9; ++i) acc[i] += sc[i * 1024 + ks * 128 + k0 + u] * wq[u]; }
.LBB0_19:
	ds_read_b128 v[32:35], v122 offset:0
	ds_read_b128 v[36:39], v122 offset:4096
	ds_read_b128 v[40:43], v122 offset:8192
	ds_read_b128 v[44:47], v122 offset:12288
	ds_read_b128 v[48:51], v122 offset:16384
	ds_read_b128 v[52:55], v122 offset:20480
	ds_read_b128 v[56:59], v122 offset:24576
	ds_read_b128 v[60:63], v122 offset:28672
	ds_read_b128 v[64:67], v122 offset:32768
	s_waitcnt vmcnt(32)
	global_load_dword v162, v[128:129], off
	v_lshl_add_u64 v[128:129], v[128:129], 0, s[18:19]
	global_load_dword v163, v[128:129], off
	v_lshl_add_u64 v[128:129], v[128:129], 0, s[18:19]
	global_load_dword v164, v[128:129], off
	v_lshl_add_u64 v[128:129], v[128:129], 0, s[18:19]
	global_load_dword v165, v[128:129], off
	v_lshl_add_u64 v[128:129], v[128:129], 0, s[18:19]
	global_load_dword v166, v[128:129], off
	v_lshl_add_u64 v[128:129], v[128:129], 0, s[18:19]
	global_load_dword v167, v[128:129], off
	v_lshl_add_u64 v[128:129], v[128:129], 0, s[18:19]
	global_load_dword v168, v[128:129], off
	v_lshl_add_u64 v[128:129], v[128:129], 0, s[18:19]
	global_load_dword v169, v[128:129], off
	v_lshl_add_u64 v[128:129], v[128:129], 0, s[18:19]
	global_load_dword v170, v[128:129], off
	v_lshl_add_u64 v[128:129], v[128:129], 0, s[18:19]
	global_load_dword v171, v[128:129], off
	v_lshl_add_u64 v[128:129], v[128:129], 0, s[18:19]
	global_load_dword v172, v[128:129], off
	v_lshl_add_u64 v[128:129], v[128:129], 0, s[18:19]
	global_load_dword v173, v[128:129], off
	v_lshl_add_u64 v[128:129], v[128:129], 0, s[18:19]
	global_load_dword v174, v[128:129], off
	v_lshl_add_u64 v[128:129], v[128:129], 0, s[18:19]
	global_load_dword v175, v[128:129], off
	v_lshl_add_u64 v[128:129], v[128:129], 0, s[18:19]
	global_load_dword v176, v[128:129], off
	v_lshl_add_u64 v[128:129], v[128:129], 0, s[18:19]
	global_load_dword v177, v[128:129], off
	v_lshl_add_u64 v[128:129], v[128:129], 0, s[18:19]
	s_waitcnt lgkmcnt(0)
	ds_read_b128 v[68:71], v122 offset:16
	ds_read_b128 v[72:75], v122 offset:4112
	ds_read_b128 v[76:79], v122 offset:8208
	ds_read_b128 v[80:83], v122 offset:12304
	ds_read_b128 v[84:87], v122 offset:16400
	ds_read_b128 v[88:91], v122 offset:20496
	ds_read_b128 v[92:95], v122 offset:24592
	ds_read_b128 v[96:99], v122 offset:28688
	ds_read_b128 v[100:103], v122 offset:32784
	v_fmac_f32_e32 v130, v0, v32
	v_fmac_f32_e32 v131, v0, v36
	v_fmac_f32_e32 v132, v0, v40
	v_fmac_f32_e32 v133, v0, v44
	v_fmac_f32_e32 v134, v0, v48
	v_fmac_f32_e32 v135, v0, v52
	v_fmac_f32_e32 v136, v0, v56
	v_fmac_f32_e32 v137, v0, v60
	v_fmac_f32_e32 v127, v0, v64
	v_fmac_f32_e32 v130, v1, v33
	v_fmac_f32_e32 v131, v1, v37
	v_fmac_f32_e32 v132, v1, v41
	v_fmac_f32_e32 v133, v1, v45
	v_fmac_f32_e32 v134, v1, v49
	v_fmac_f32_e32 v135, v1, v53
	v_fmac_f32_e32 v136, v1, v57
	v_fmac_f32_e32 v137, v1, v61
	v_fmac_f32_e32 v127, v1, v65
	v_fmac_f32_e32 v130, v2, v34
	v_fmac_f32_e32 v131, v2, v38
	v_fmac_f32_e32 v132, v2, v42
	v_fmac_f32_e32 v133, v2, v46
	v_fmac_f32_e32 v134, v2, v50
	v_fmac_f32_e32 v135, v2, v54
	v_fmac_f32_e32 v136, v2, v58
	v_fmac_f32_e32 v137, v2, v62
	v_fmac_f32_e32 v127, v2, v66
	v_fmac_f32_e32 v130, v3, v35
	v_fmac_f32_e32 v131, v3, v39
	v_fmac_f32_e32 v132, v3, v43
	v_fmac_f32_e32 v133, v3, v47
	v_fmac_f32_e32 v134, v3, v51
	v_fmac_f32_e32 v135, v3, v55
	v_fmac_f32_e32 v136, v3, v59
	v_fmac_f32_e32 v137, v3, v63
	v_fmac_f32_e32 v127, v3, v67
	s_waitcnt lgkmcnt(0)
	ds_read_b128 v[32:35], v122 offset:32
	ds_read_b128 v[36:39], v122 offset:4128
	ds_read_b128 v[40:43], v122 offset:8224
	ds_read_b128 v[44:47], v122 offset:12320
	ds_read_b128 v[48:51], v122 offset:16416
	ds_read_b128 v[52:55], v122 offset:20512
	ds_read_b128 v[56:59], v122 offset:24608
	ds_read_b128 v[60:63], v122 offset:28704
	ds_read_b128 v[64:67], v122 offset:32800
	v_fmac_f32_e32 v130, v4, v68
	v_fmac_f32_e32 v131, v4, v72
	v_fmac_f32_e32 v132, v4, v76
	v_fmac_f32_e32 v133, v4, v80
	v_fmac_f32_e32 v134, v4, v84
	v_fmac_f32_e32 v135, v4, v88
	v_fmac_f32_e32 v136, v4, v92
	v_fmac_f32_e32 v137, v4, v96
	v_mul_f32_e32 v104, v4, v100
	v_add_f32_e32 v127, v127, v104
	v_fmac_f32_e32 v130, v5, v69
	v_fmac_f32_e32 v131, v5, v73
	v_fmac_f32_e32 v132, v5, v77
	v_fmac_f32_e32 v133, v5, v81
	v_fmac_f32_e32 v134, v5, v85
	v_fmac_f32_e32 v135, v5, v89
	v_fmac_f32_e32 v136, v5, v93
	v_fmac_f32_e32 v137, v5, v97
	v_mul_f32_e32 v104, v5, v101
	v_add_f32_e32 v127, v127, v104
	v_fmac_f32_e32 v130, v6, v70
	v_fmac_f32_e32 v131, v6, v74
	v_fmac_f32_e32 v132, v6, v78
	v_fmac_f32_e32 v133, v6, v82
	v_fmac_f32_e32 v134, v6, v86
	v_fmac_f32_e32 v135, v6, v90
	v_fmac_f32_e32 v136, v6, v94
	v_fmac_f32_e32 v137, v6, v98
	v_mul_f32_e32 v104, v6, v102
	v_add_f32_e32 v127, v127, v104
	v_fmac_f32_e32 v130, v7, v71
	v_fmac_f32_e32 v131, v7, v75
	v_fmac_f32_e32 v132, v7, v79
	v_fmac_f32_e32 v133, v7, v83
	v_fmac_f32_e32 v134, v7, v87
	v_fmac_f32_e32 v135, v7, v91
	v_fmac_f32_e32 v136, v7, v95
	v_fmac_f32_e32 v137, v7, v99
	v_mul_f32_e32 v104, v7, v103
	v_add_f32_e32 v127, v127, v104
	s_waitcnt lgkmcnt(0)
; __device__ __forceinline__ void phase0(int wv, const Params& p, LAS unsigned char* lds, int cb_first, int cb_stride, int cb_lo, int cb_hi, bool do_rope) {
;     ...
;         for (int k0 = 0; k0 < 128; k0 += 16) { float wq[16];
; #pragma unroll
;             for (int u = 0; u < 16; ++u) wq[u] = w[(size_t)(k0 + u) * 6144];
; #pragma unroll
;             for (int u = 0; u < 16; ++u)
; #pragma unroll
;                 for (int i = 0; i < 9; ++i) acc[i] += sc[i * 1024 + ks * 128 + k0 + u] * wq[u]; }
	ds_read_b128 v[68:71], v122 offset:48
	ds_read_b128 v[72:75], v122 offset:4144
	ds_read_b128 v[76:79], v122 offset:8240
	ds_read_b128 v[80:83], v122 offset:12336
	ds_read_b128 v[84:87], v122 offset:16432
	ds_read_b128 v[88:91], v122 offset:20528
	ds_read_b128 v[92:95], v122 offset:24624
	ds_read_b128 v[96:99], v122 offset:28720
	ds_read_b128 v[100:103], v122 offset:32816
	v_fmac_f32_e32 v130, v8, v32
	v_fmac_f32_e32 v131, v8, v36
	v_fmac_f32_e32 v132, v8, v40
	v_fmac_f32_e32 v133, v8, v44
	v_fmac_f32_e32 v134, v8, v48
	v_fmac_f32_e32 v135, v8, v52
	v_fmac_f32_e32 v136, v8, v56
	v_fmac_f32_e32 v137, v8, v60
	v_mul_f32_e32 v104, v8, v64
	v_add_f32_e32 v127, v127, v104
	v_fmac_f32_e32 v130, v9, v33
	v_fmac_f32_e32 v131, v9, v37
	v_fmac_f32_e32 v132, v9, v41
	v_fmac_f32_e32 v133, v9, v45
	v_fmac_f32_e32 v134, v9, v49
	v_fmac_f32_e32 v135, v9, v53
	v_fmac_f32_e32 v136, v9, v57
	v_fmac_f32_e32 v137, v9, v61
	v_mul_f32_e32 v104, v9, v65
	v_add_f32_e32 v127, v127, v104
	v_fmac_f32_e32 v130, v10, v34
	v_fmac_f32_e32 v131, v10, v38
	v_fmac_f32_e32 v132, v10, v42
	v_fmac_f32_e32 v133, v10, v46
	v_fmac_f32_e32 v134, v10, v50
	v_fmac_f32_e32 v135, v10, v54
	v_fmac_f32_e32 v136, v10, v58
	v_fmac_f32_e32 v137, v10, v62
	v_mul_f32_e32 v104, v10, v66
	v_add_f32_e32 v127, v127, v104
	v_fmac_f32_e32 v130, v11, v35
	v_fmac_f32_e32 v131, v11, v39
	v_fmac_f32_e32 v132, v11, v43
	v_fmac_f32_e32 v133, v11, v47
	v_fmac_f32_e32 v134, v11, v51
	v_fmac_f32_e32 v135, v11, v55
	v_fmac_f32_e32 v136, v11, v59
	v_fmac_f32_e32 v137, v11, v63
	v_mul_f32_e32 v104, v11, v67
	v_add_f32_e32 v127, v127, v104
	s_waitcnt lgkmcnt(0)
	v_fmac_f32_e32 v130, v12, v68
	v_fmac_f32_e32 v131, v12, v72
	v_fmac_f32_e32 v132, v12, v76
	v_fmac_f32_e32 v133, v12, v80
	v_fmac_f32_e32 v134, v12, v84
	v_fmac_f32_e32 v135, v12, v88
	v_fmac_f32_e32 v136, v12, v92
	v_fmac_f32_e32 v137, v12, v96
	v_mul_f32_e32 v104, v12, v100
	v_add_f32_e32 v127, v127, v104
	v_fmac_f32_e32 v130, v13, v69
	v_fmac_f32_e32 v131, v13, v73
	v_fmac_f32_e32 v132, v13, v77
	v_fmac_f32_e32 v133, v13, v81
	v_fmac_f32_e32 v134, v13, v85
	v_fmac_f32_e32 v135, v13, v89
	v_fmac_f32_e32 v136, v13, v93
	v_fmac_f32_e32 v137, v13, v97
	v_mul_f32_e32 v104, v13, v101
	v_add_f32_e32 v127, v127, v104
	v_fmac_f32_e32 v130, v14, v70
	v_fmac_f32_e32 v131, v14, v74
	v_fmac_f32_e32 v132, v14, v78
	v_fmac_f32_e32 v133, v14, v82
	v_fmac_f32_e32 v134, v14, v86
	v_fmac_f32_e32 v135, v14, v90
	v_fmac_f32_e32 v136, v14, v94
	v_fmac_f32_e32 v137, v14, v98
	v_mul_f32_e32 v104, v14, v102
	v_add_f32_e32 v127, v127, v104
	v_fmac_f32_e32 v130, v15, v71
	v_fmac_f32_e32 v131, v15, v75
	v_fmac_f32_e32 v132, v15, v79
	v_fmac_f32_e32 v133, v15, v83
	v_fmac_f32_e32 v134, v15, v87
	v_fmac_f32_e32 v135, v15, v91
	v_fmac_f32_e32 v136, v15, v95
	v_fmac_f32_e32 v137, v15, v99
	v_mul_f32_e32 v104, v15, v103
	v_add_f32_e32 v127, v127, v104
	v_add_u32_e32 v122, 64, v122
	ds_read_b128 v[32:35], v122 offset:0
	ds_read_b128 v[36:39], v122 offset:4096
	ds_read_b128 v[40:43], v122 offset:8192
	ds_read_b128 v[44:47], v122 offset:12288
	ds_read_b128 v[48:51], v122 offset:16384
	ds_read_b128 v[52:55], v122 offset:20480
	ds_read_b128 v[56:59], v122 offset:24576
	ds_read_b128 v[60:63], v122 offset:28672
	ds_read_b128 v[64:67], v122 offset:32768
	s_waitcnt vmcnt(32)
	global_load_dword v0, v[128:129], off
	v_lshl_add_u64 v[128:129], v[128:129], 0, s[18:19]
	global_load_dword v1, v[128:129], off
	v_lshl_add_u64 v[128:129], v[128:129], 0, s[18:19]
	global_load_dword v2, v[128:129], off
	v_lshl_add_u64 v[128:129], v[128:129], 0, s[18:19]
	global_load_dword v3, v[128:129], off
	v_lshl_add_u64 v[128:129], v[128:129], 0, s[18:19]
	global_load_dword v4, v[128:129], off
	v_lshl_add_u64 v[128:129], v[128:129], 0, s[18:19]
	global_load_dword v5, v[128:129], off
	v_lshl_add_u64 v[128:129], v[128:129], 0, s[18:19]
	global_load_dword v6, v[128:129], off
	v_lshl_add_u64 v[128:129], v[128:129], 0, s[18:19]
	global_load_dword v7, v[128:129], off
	v_lshl_add_u64 v[128:129], v[128:129], 0, s[18:19]
	global_load_dword v8, v[128:129], off
	v_lshl_add_u64 v[128:129], v[128:129], 0, s[18:19]
	global_load_dword v9, v[128:129], off
	v_lshl_add_u64 v[128:129], v[128:129], 0, s[18:19]
	global_load_dword v10, v[128:129], off
	v_lshl_add_u64 v[128:129], v[128:129], 0, s[18:19]
	global_load_dword v11, v[128:129], off
	v_lshl_add_u64 v[128:129], v[128:129], 0, s[18:19]
	global_load_dword v12, v[128:129], off
	v_lshl_add_u64 v[128:129], v[128:129], 0, s[18:19]
	global_load_dword v13, v[128:129], off
	v_lshl_add_u64 v[128:129], v[128:129], 0, s[18:19]
	global_load_dword v14, v[128:129], off
	v_lshl_add_u64 v[128:129], v[128:129], 0, s[18:19]
	global_load_dword v15, v[128:129], off
	v_lshl_add_u64 v[128:129], v[128:129], 0, s[18:19]
	s_waitcnt lgkmcnt(0)
	ds_read_b128 v[68:71], v122 offset:16
	ds_read_b128 v[72:75], v122 offset:4112
	ds_read_b128 v[76:79], v122 offset:8208
	ds_read_b128 v[80:83], v122 offset:12304
	ds_read_b128 v[84:87], v122 offset:16400
	ds_read_b128 v[88:91], v122 offset:20496
	ds_read_b128 v[92:95], v122 offset:24592
	ds_read_b128 v[96:99], v122 offset:28688
	ds_read_b128 v[100:103], v122 offset:32784
	v_fmac_f32_e32 v130, v16, v32
	v_fmac_f32_e32 v131, v16, v36
	v_fmac_f32_e32 v132, v16, v40
	v_fmac_f32_e32 v133, v16, v44
	v_fmac_f32_e32 v134, v16, v48
	v_fmac_f32_e32 v135, v16, v52
	v_fmac_f32_e32 v136, v16, v56
	v_fmac_f32_e32 v137, v16, v60
	v_fmac_f32_e32 v127, v16, v64
	v_fmac_f32_e32 v130, v17, v33
	v_fmac_f32_e32 v131, v17, v37
	v_fmac_f32_e32 v132, v17, v41
	v_fmac_f32_e32 v133, v17, v45
	v_fmac_f32_e32 v134, v17, v49
	v_fmac_f32_e32 v135, v17, v53
	v_fmac_f32_e32 v136, v17, v57
	v_fmac_f32_e32 v137, v17, v61
	v_fmac_f32_e32 v127, v17, v65
	v_fmac_f32_e32 v130, v18, v34
	v_fmac_f32_e32 v131, v18, v38
	v_fmac_f32_e32 v132, v18, v42
	v_fmac_f32_e32 v133, v18, v46
	v_fmac_f32_e32 v134, v18, v50
	v_fmac_f32_e32 v135, v18, v54
	v_fmac_f32_e32 v136, v18, v58
	v_fmac_f32_e32 v137, v18, v62
	v_fmac_f32_e32 v127, v18, v66
	v_fmac_f32_e32 v130, v19, v35
	v_fmac_f32_e32 v131, v19, v39
	v_fmac_f32_e32 v132, v19, v43
	v_fmac_f32_e32 v133, v19, v47
	v_fmac_f32_e32 v134, v19, v51
	v_fmac_f32_e32 v135, v19, v55
	v_fmac_f32_e32 v136, v19, v59
	v_fmac_f32_e32 v137, v19, v63
	v_fmac_f32_e32 v127, v19, v67
	s_waitcnt lgkmcnt(0)
; __device__ __forceinline__ void phase0(int wv, const Params& p, LAS unsigned char* lds, int cb_first, int cb_stride, int cb_lo, int cb_hi, bool do_rope) {
;     ...
;         for (int k0 = 0; k0 < 128; k0 += 16) { float wq[16];
; #pragma unroll
;             for (int u = 0; u < 16; ++u) wq[u] = w[(size_t)(k0 + u) * 6144];
; #pragma unroll
;             for (int u = 0; u < 16; ++u)
; #pragma unroll
;                 for (int i = 0; i < 9; ++i) acc[i] += sc[i * 1024 + ks * 128 + k0 + u] * wq[u]; }
	ds_read_b128 v[32:35], v122 offset:32
	ds_read_b128 v[36:39], v122 offset:4128
	ds_read_b128 v[40:43], v122 offset:8224
	ds_read_b128 v[44:47], v122 offset:12320
	ds_read_b128 v[48:51], v122 offset:16416
	ds_read_b128 v[52:55], v122 offset:20512
	ds_read_b128 v[56:59], v122 offset:24608
	ds_read_b128 v[60:63], v122 offset:28704
	ds_read_b128 v[64:67], v122 offset:32800
	v_fmac_f32_e32 v130, v20, v68
	v_fmac_f32_e32 v131, v20, v72
	v_fmac_f32_e32 v132, v20, v76
	v_fmac_f32_e32 v133, v20, v80
	v_fmac_f32_e32 v134, v20, v84
	v_fmac_f32_e32 v135, v20, v88
	v_fmac_f32_e32 v136, v20, v92
	v_fmac_f32_e32 v137, v20, v96
	v_mul_f32_e32 v104, v20, v100
	v_add_f32_e32 v127, v127, v104
	v_fmac_f32_e32 v130, v21, v69
	v_fmac_f32_e32 v131, v21, v73
	v_fmac_f32_e32 v132, v21, v77
	v_fmac_f32_e32 v133, v21, v81
	v_fmac_f32_e32 v134, v21, v85
	v_fmac_f32_e32 v135, v21, v89
	v_fmac_f32_e32 v136, v21, v93
	v_fmac_f32_e32 v137, v21, v97
	v_mul_f32_e32 v104, v21, v101
	v_add_f32_e32 v127, v127, v104
	v_fmac_f32_e32 v130, v22, v70
	v_fmac_f32_e32 v131, v22, v74
	v_fmac_f32_e32 v132, v22, v78
	v_fmac_f32_e32 v133, v22, v82
	v_fmac_f32_e32 v134, v22, v86
	v_fmac_f32_e32 v135, v22, v90
	v_fmac_f32_e32 v136, v22, v94
	v_fmac_f32_e32 v137, v22, v98
	v_mul_f32_e32 v104, v22, v102
	v_add_f32_e32 v127, v127, v104
	v_fmac_f32_e32 v130, v23, v71
	v_fmac_f32_e32 v131, v23, v75
	v_fmac_f32_e32 v132, v23, v79
	v_fmac_f32_e32 v133, v23, v83
	v_fmac_f32_e32 v134, v23, v87
	v_fmac_f32_e32 v135, v23, v91
	v_fmac_f32_e32 v136, v23, v95
	v_fmac_f32_e32 v137, v23, v99
	v_mul_f32_e32 v104, v23, v103
	v_add_f32_e32 v127, v127, v104
	s_waitcnt lgkmcnt(0)
	ds_read_b128 v[68:71], v122 offset:48
	ds_read_b128 v[72:75], v122 offset:4144
	ds_read_b128 v[76:79], v122 offset:8240
	ds_read_b128 v[80:83], v122 offset:12336
	ds_read_b128 v[84:87], v122 offset:16432
	ds_read_b128 v[88:91], v122 offset:20528
	ds_read_b128 v[92:95], v122 offset:24624
	ds_read_b128 v[96:99], v122 offset:28720
	ds_read_b128 v[100:103], v122 offset:32816
	v_fmac_f32_e32 v130, v24, v32
	v_fmac_f32_e32 v131, v24, v36
	v_fmac_f32_e32 v132, v24, v40
	v_fmac_f32_e32 v133, v24, v44
	v_fmac_f32_e32 v134, v24, v48
	v_fmac_f32_e32 v135, v24, v52
	v_fmac_f32_e32 v136, v24, v56
	v_fmac_f32_e32 v137, v24, v60
	v_mul_f32_e32 v104, v24, v64
	v_add_f32_e32 v127, v127, v104
	v_fmac_f32_e32 v130, v25, v33
	v_fmac_f32_e32 v131, v25, v37
	v_fmac_f32_e32 v132, v25, v41
	v_fmac_f32_e32 v133, v25, v45
	v_fmac_f32_e32 v134, v25, v49
	v_fmac_f32_e32 v135, v25, v53
	v_fmac_f32_e32 v136, v25, v57
	v_fmac_f32_e32 v137, v25, v61
	v_mul_f32_e32 v104, v25, v65
	v_add_f32_e32 v127, v127, v104
	v_fmac_f32_e32 v130, v26, v34
	v_fmac_f32_e32 v131, v26, v38
	v_fmac_f32_e32 v132, v26, v42
	v_fmac_f32_e32 v133, v26, v46
	v_fmac_f32_e32 v134, v26, v50
	v_fmac_f32_e32 v135, v26, v54
	v_fmac_f32_e32 v136, v26, v58
	v_fmac_f32_e32 v137, v26, v62
	v_mul_f32_e32 v104, v26, v66
	v_add_f32_e32 v127, v127, v104
	v_fmac_f32_e32 v130, v27, v35
	v_fmac_f32_e32 v131, v27, v39
	v_fmac_f32_e32 v132, v27, v43
	v_fmac_f32_e32 v133, v27, v47
	v_fmac_f32_e32 v134, v27, v51
	v_fmac_f32_e32 v135, v27, v55
	v_fmac_f32_e32 v136, v27, v59
	v_fmac_f32_e32 v137, v27, v63
	v_mul_f32_e32 v104, v27, v67
	v_add_f32_e32 v127, v127, v104
	s_waitcnt lgkmcnt(0)
	v_fmac_f32_e32 v130, v28, v68
	v_fmac_f32_e32 v131, v28, v72
	v_fmac_f32_e32 v132, v28, v76
	v_fmac_f32_e32 v133, v28, v80
	v_fmac_f32_e32 v134, v28, v84
	v_fmac_f32_e32 v135, v28, v88
	v_fmac_f32_e32 v136, v28, v92
	v_fmac_f32_e32 v137, v28, v96
	v_mul_f32_e32 v104, v28, v100
	v_add_f32_e32 v127, v127, v104
	v_fmac_f32_e32 v130, v29, v69
	v_fmac_f32_e32 v131, v29, v73
	v_fmac_f32_e32 v132, v29, v77
	v_fmac_f32_e32 v133, v29, v81
	v_fmac_f32_e32 v134, v29, v85
	v_fmac_f32_e32 v135, v29, v89
	v_fmac_f32_e32 v136, v29, v93
	v_fmac_f32_e32 v137, v29, v97
	v_mul_f32_e32 v104, v29, v101
	v_add_f32_e32 v127, v127, v104
	v_fmac_f32_e32 v130, v30, v70
	v_fmac_f32_e32 v131, v30, v74
	v_fmac_f32_e32 v132, v30, v78
	v_fmac_f32_e32 v133, v30, v82
	v_fmac_f32_e32 v134, v30, v86
	v_fmac_f32_e32 v135, v30, v90
	v_fmac_f32_e32 v136, v30, v94
	v_fmac_f32_e32 v137, v30, v98
	v_mul_f32_e32 v104, v30, v102
	v_add_f32_e32 v127, v127, v104
	v_fmac_f32_e32 v130, v31, v71
	v_fmac_f32_e32 v131, v31, v75
	v_fmac_f32_e32 v132, v31, v79
	v_fmac_f32_e32 v133, v31, v83
	v_fmac_f32_e32 v134, v31, v87
	v_fmac_f32_e32 v135, v31, v91
	v_fmac_f32_e32 v136, v31, v95
	v_fmac_f32_e32 v137, v31, v99
	v_mul_f32_e32 v104, v31, v103
	v_add_f32_e32 v127, v127, v104
	v_add_u32_e32 v122, 64, v122
	ds_read_b128 v[32:35], v122 offset:0
	ds_read_b128 v[36:39], v122 offset:4096
	ds_read_b128 v[40:43], v122 offset:8192
	ds_read_b128 v[44:47], v122 offset:12288
	ds_read_b128 v[48:51], v122 offset:16384
	ds_read_b128 v[52:55], v122 offset:20480
	ds_read_b128 v[56:59], v122 offset:24576
	ds_read_b128 v[60:63], v122 offset:28672
	ds_read_b128 v[64:67], v122 offset:32768
	s_waitcnt vmcnt(32)
; __device__ __forceinline__ void phase0(int wv, const Params& p, LAS unsigned char* lds, int cb_first, int cb_stride, int cb_lo, int cb_hi, bool do_rope) {
;     ...
;         for (int k0 = 0; k0 < 128; k0 += 16) { float wq[16];
; #pragma unroll
;             for (int u = 0; u < 16; ++u) wq[u] = w[(size_t)(k0 + u) * 6144];
; #pragma unroll
;             for (int u = 0; u < 16; ++u)
; #pragma unroll
;                 for (int i = 0; i < 9; ++i) acc[i] += sc[i * 1024 + ks * 128 + k0 + u] * wq[u]; }
	global_load_dword v16, v[128:129], off
	v_lshl_add_u64 v[128:129], v[128:129], 0, s[18:19]
	global_load_dword v17, v[128:129], off
	v_lshl_add_u64 v[128:129], v[128:129], 0, s[18:19]
	global_load_dword v18, v[128:129], off
	v_lshl_add_u64 v[128:129], v[128:129], 0, s[18:19]
	global_load_dword v19, v[128:129], off
	v_lshl_add_u64 v[128:129], v[128:129], 0, s[18:19]
	global_load_dword v20, v[128:129], off
	v_lshl_add_u64 v[128:129], v[128:129], 0, s[18:19]
	global_load_dword v21, v[128:129], off
	v_lshl_add_u64 v[128:129], v[128:129], 0, s[18:19]
	global_load_dword v22, v[128:129], off
	v_lshl_add_u64 v[128:129], v[128:129], 0, s[18:19]
	global_load_dword v23, v[128:129], off
	v_lshl_add_u64 v[128:129], v[128:129], 0, s[18:19]
	global_load_dword v24, v[128:129], off
	v_lshl_add_u64 v[128:129], v[128:129], 0, s[18:19]
	global_load_dword v25, v[128:129], off
	v_lshl_add_u64 v[128:129], v[128:129], 0, s[18:19]
	global_load_dword v26, v[128:129], off
	v_lshl_add_u64 v[128:129], v[128:129], 0, s[18:19]
	global_load_dword v27, v[128:129], off
	v_lshl_add_u64 v[128:129], v[128:129], 0, s[18:19]
	global_load_dword v28, v[128:129], off
	v_lshl_add_u64 v[128:129], v[128:129], 0, s[18:19]
	global_load_dword v29, v[128:129], off
	v_lshl_add_u64 v[128:129], v[128:129], 0, s[18:19]
	global_load_dword v30, v[128:129], off
	v_lshl_add_u64 v[128:129], v[128:129], 0, s[18:19]
	global_load_dword v31, v[128:129], off
	v_lshl_add_u64 v[128:129], v[128:129], 0, s[18:19]
	s_waitcnt lgkmcnt(0)
	ds_read_b128 v[68:71], v122 offset:16
	ds_read_b128 v[72:75], v122 offset:4112
	ds_read_b128 v[76:79], v122 offset:8208
	ds_read_b128 v[80:83], v122 offset:12304
	ds_read_b128 v[84:87], v122 offset:16400
	ds_read_b128 v[88:91], v122 offset:20496
	ds_read_b128 v[92:95], v122 offset:24592
	ds_read_b128 v[96:99], v122 offset:28688
	ds_read_b128 v[100:103], v122 offset:32784
	v_fmac_f32_e32 v130, v146, v32
	v_fmac_f32_e32 v131, v146, v36
	v_fmac_f32_e32 v132, v146, v40
	v_fmac_f32_e32 v133, v146, v44
	v_fmac_f32_e32 v134, v146, v48
	v_fmac_f32_e32 v135, v146, v52
	v_fmac_f32_e32 v136, v146, v56
	v_fmac_f32_e32 v137, v146, v60
	v_fmac_f32_e32 v127, v146, v64
	v_fmac_f32_e32 v130, v147, v33
	v_fmac_f32_e32 v131, v147, v37
	v_fmac_f32_e32 v132, v147, v41
	v_fmac_f32_e32 v133, v147, v45
	v_fmac_f32_e32 v134, v147, v49
	v_fmac_f32_e32 v135, v147, v53
	v_fmac_f32_e32 v136, v147, v57
	v_fmac_f32_e32 v137, v147, v61
	v_fmac_f32_e32 v127, v147, v65
	v_fmac_f32_e32 v130, v148, v34
	v_fmac_f32_e32 v131, v148, v38
	v_fmac_f32_e32 v132, v148, v42
	v_fmac_f32_e32 v133, v148, v46
	v_fmac_f32_e32 v134, v148, v50
	v_fmac_f32_e32 v135, v148, v54
	v_fmac_f32_e32 v136, v148, v58
	v_fmac_f32_e32 v137, v148, v62
	v_fmac_f32_e32 v127, v148, v66
	v_fmac_f32_e32 v130, v149, v35
	v_fmac_f32_e32 v131, v149, v39
	v_fmac_f32_e32 v132, v149, v43
	v_fmac_f32_e32 v133, v149, v47
	v_fmac_f32_e32 v134, v149, v51
	v_fmac_f32_e32 v135, v149, v55
	v_fmac_f32_e32 v136, v149, v59
	v_fmac_f32_e32 v137, v149, v63
	v_fmac_f32_e32 v127, v149, v67
	s_waitcnt lgkmcnt(0)
	ds_read_b128 v[32:35], v122 offset:32
	ds_read_b128 v[36:39], v122 offset:4128
	ds_read_b128 v[40:43], v122 offset:8224
	ds_read_b128 v[44:47], v122 offset:12320
	ds_read_b128 v[48:51], v122 offset:16416
	ds_read_b128 v[52:55], v122 offset:20512
	ds_read_b128 v[56:59], v122 offset:24608
	ds_read_b128 v[60:63], v122 offset:28704
	ds_read_b128 v[64:67], v122 offset:32800
	v_fmac_f32_e32 v130, v150, v68
	v_fmac_f32_e32 v131, v150, v72
	v_fmac_f32_e32 v132, v150, v76
	v_fmac_f32_e32 v133, v150, v80
	v_fmac_f32_e32 v134, v150, v84
	v_fmac_f32_e32 v135, v150, v88
	v_fmac_f32_e32 v136, v150, v92
	v_fmac_f32_e32 v137, v150, v96
	v_mul_f32_e32 v104, v150, v100
	v_add_f32_e32 v127, v127, v104
	v_fmac_f32_e32 v130, v151, v69
	v_fmac_f32_e32 v131, v151, v73
	v_fmac_f32_e32 v132, v151, v77
	v_fmac_f32_e32 v133, v151, v81
	v_fmac_f32_e32 v134, v151, v85
	v_fmac_f32_e32 v135, v151, v89
	v_fmac_f32_e32 v136, v151, v93
	v_fmac_f32_e32 v137, v151, v97
	v_mul_f32_e32 v104, v151, v101
	v_add_f32_e32 v127, v127, v104
	v_fmac_f32_e32 v130, v152, v70
	v_fmac_f32_e32 v131, v152, v74
	v_fmac_f32_e32 v132, v152, v78
	v_fmac_f32_e32 v133, v152, v82
	v_fmac_f32_e32 v134, v152, v86
	v_fmac_f32_e32 v135, v152, v90
	v_fmac_f32_e32 v136, v152, v94
	v_fmac_f32_e32 v137, v152, v98
	v_mul_f32_e32 v104, v152, v102
	v_add_f32_e32 v127, v127, v104
	v_fmac_f32_e32 v130, v153, v71
	v_fmac_f32_e32 v131, v153, v75
	v_fmac_f32_e32 v132, v153, v79
	v_fmac_f32_e32 v133, v153, v83
	v_fmac_f32_e32 v134, v153, v87
	v_fmac_f32_e32 v135, v153, v91
	v_fmac_f32_e32 v136, v153, v95
	v_fmac_f32_e32 v137, v153, v99
	v_mul_f32_e32 v104, v153, v103
	v_add_f32_e32 v127, v127, v104
	s_waitcnt lgkmcnt(0)
	ds_read_b128 v[68:71], v122 offset:48
	ds_read_b128 v[72:75], v122 offset:4144
	ds_read_b128 v[76:79], v122 offset:8240
	ds_read_b128 v[80:83], v122 offset:12336
	ds_read_b128 v[84:87], v122 offset:16432
	ds_read_b128 v[88:91], v122 offset:20528
	ds_read_b128 v[92:95], v122 offset:24624
	ds_read_b128 v[96:99], v122 offset:28720
	ds_read_b128 v[100:103], v122 offset:32816
	v_fmac_f32_e32 v130, v154, v32
	v_fmac_f32_e32 v131, v154, v36
	v_fmac_f32_e32 v132, v154, v40
	v_fmac_f32_e32 v133, v154, v44
	v_fmac_f32_e32 v134, v154, v48
	v_fmac_f32_e32 v135, v154, v52
	v_fmac_f32_e32 v136, v154, v56
	v_fmac_f32_e32 v137, v154, v60
	v_mul_f32_e32 v104, v154, v64
	v_add_f32_e32 v127, v127, v104
	v_fmac_f32_e32 v130, v155, v33
	v_fmac_f32_e32 v131, v155, v37
	v_fmac_f32_e32 v132, v155, v41
	v_fmac_f32_e32 v133, v155, v45
	v_fmac_f32_e32 v134, v155, v49
	v_fmac_f32_e32 v135, v155, v53
	v_fmac_f32_e32 v136, v155, v57
	v_fmac_f32_e32 v137, v155, v61
	v_mul_f32_e32 v104, v155, v65
	v_add_f32_e32 v127, v127, v104
	v_fmac_f32_e32 v130, v156, v34
	v_fmac_f32_e32 v131, v156, v38
	v_fmac_f32_e32 v132, v156, v42
	v_fmac_f32_e32 v133, v156, v46
	v_fmac_f32_e32 v134, v156, v50
	v_fmac_f32_e32 v135, v156, v54
	v_fmac_f32_e32 v136, v156, v58
	v_fmac_f32_e32 v137, v156, v62
	v_mul_f32_e32 v104, v156, v66
	v_add_f32_e32 v127, v127, v104
	v_fmac_f32_e32 v130, v157, v35
	v_fmac_f32_e32 v131, v157, v39
	v_fmac_f32_e32 v132, v157, v43
	v_fmac_f32_e32 v133, v157, v47
	v_fmac_f32_e32 v134, v157, v51
	v_fmac_f32_e32 v135, v157, v55
	v_fmac_f32_e32 v136, v157, v59
	v_fmac_f32_e32 v137, v157, v63
	v_mul_f32_e32 v104, v157, v67
	v_add_f32_e32 v127, v127, v104
	s_waitcnt lgkmcnt(0)
; __device__ __forceinline__ void phase0(int wv, const Params& p, LAS unsigned char* lds, int cb_first, int cb_stride, int cb_lo, int cb_hi, bool do_rope) {
;     ...
;         for (int k0 = 0; k0 < 128; k0 += 16) { float wq[16];
; #pragma unroll
;             for (int u = 0; u < 16; ++u) wq[u] = w[(size_t)(k0 + u) * 6144];
; #pragma unroll
;             for (int u = 0; u < 16; ++u)
; #pragma unroll
;                 for (int i = 0; i < 9; ++i) acc[i] += sc[i * 1024 + ks * 128 + k0 + u] * wq[u]; }
	v_fmac_f32_e32 v130, v158, v68
	v_fmac_f32_e32 v131, v158, v72
	v_fmac_f32_e32 v132, v158, v76
	v_fmac_f32_e32 v133, v158, v80
	v_fmac_f32_e32 v134, v158, v84
	v_fmac_f32_e32 v135, v158, v88
	v_fmac_f32_e32 v136, v158, v92
	v_fmac_f32_e32 v137, v158, v96
	v_mul_f32_e32 v104, v158, v100
	v_add_f32_e32 v127, v127, v104
	v_fmac_f32_e32 v130, v159, v69
	v_fmac_f32_e32 v131, v159, v73
	v_fmac_f32_e32 v132, v159, v77
	v_fmac_f32_e32 v133, v159, v81
	v_fmac_f32_e32 v134, v159, v85
	v_fmac_f32_e32 v135, v159, v89
	v_fmac_f32_e32 v136, v159, v93
	v_fmac_f32_e32 v137, v159, v97
	v_mul_f32_e32 v104, v159, v101
	v_add_f32_e32 v127, v127, v104
	v_fmac_f32_e32 v130, v160, v70
	v_fmac_f32_e32 v131, v160, v74
	v_fmac_f32_e32 v132, v160, v78
	v_fmac_f32_e32 v133, v160, v82
	v_fmac_f32_e32 v134, v160, v86
	v_fmac_f32_e32 v135, v160, v90
	v_fmac_f32_e32 v136, v160, v94
	v_fmac_f32_e32 v137, v160, v98
	v_mul_f32_e32 v104, v160, v102
	v_add_f32_e32 v127, v127, v104
	v_fmac_f32_e32 v130, v161, v71
	v_fmac_f32_e32 v131, v161, v75
	v_fmac_f32_e32 v132, v161, v79
	v_fmac_f32_e32 v133, v161, v83
	v_fmac_f32_e32 v134, v161, v87
	v_fmac_f32_e32 v135, v161, v91
	v_fmac_f32_e32 v136, v161, v95
	v_fmac_f32_e32 v137, v161, v99
	v_mul_f32_e32 v104, v161, v103
	v_add_f32_e32 v127, v127, v104
	v_add_u32_e32 v122, 64, v122
	ds_read_b128 v[32:35], v122 offset:0
	ds_read_b128 v[36:39], v122 offset:4096
	ds_read_b128 v[40:43], v122 offset:8192
	ds_read_b128 v[44:47], v122 offset:12288
	ds_read_b128 v[48:51], v122 offset:16384
	ds_read_b128 v[52:55], v122 offset:20480
	ds_read_b128 v[56:59], v122 offset:24576
	ds_read_b128 v[60:63], v122 offset:28672
	ds_read_b128 v[64:67], v122 offset:32768
	s_waitcnt vmcnt(32)
	global_load_dword v146, v[128:129], off
	v_lshl_add_u64 v[128:129], v[128:129], 0, s[18:19]
	global_load_dword v147, v[128:129], off
	v_lshl_add_u64 v[128:129], v[128:129], 0, s[18:19]
	global_load_dword v148, v[128:129], off
	v_lshl_add_u64 v[128:129], v[128:129], 0, s[18:19]
	global_load_dword v149, v[128:129], off
	v_lshl_add_u64 v[128:129], v[128:129], 0, s[18:19]
	global_load_dword v150, v[128:129], off
	v_lshl_add_u64 v[128:129], v[128:129], 0, s[18:19]
	global_load_dword v151, v[128:129], off
	v_lshl_add_u64 v[128:129], v[128:129], 0, s[18:19]
	global_load_dword v152, v[128:129], off
	v_lshl_add_u64 v[128:129], v[128:129], 0, s[18:19]
	global_load_dword v153, v[128:129], off
	v_lshl_add_u64 v[128:129], v[128:129], 0, s[18:19]
	global_load_dword v154, v[128:129], off
	v_lshl_add_u64 v[128:129], v[128:129], 0, s[18:19]
	global_load_dword v155, v[128:129], off
	v_lshl_add_u64 v[128:129], v[128:129], 0, s[18:19]
	global_load_dword v156, v[128:129], off
	v_lshl_add_u64 v[128:129], v[128:129], 0, s[18:19]
	global_load_dword v157, v[128:129], off
	v_lshl_add_u64 v[128:129], v[128:129], 0, s[18:19]
	global_load_dword v158, v[128:129], off
	v_lshl_add_u64 v[128:129], v[128:129], 0, s[18:19]
	global_load_dword v159, v[128:129], off
	v_lshl_add_u64 v[128:129], v[128:129], 0, s[18:19]
	global_load_dword v160, v[128:129], off
	v_lshl_add_u64 v[128:129], v[128:129], 0, s[18:19]
	global_load_dword v161, v[128:129], off
	v_lshl_add_u64 v[128:129], v[128:129], 0, s[18:19]
	s_waitcnt lgkmcnt(0)
	ds_read_b128 v[68:71], v122 offset:16
	ds_read_b128 v[72:75], v122 offset:4112
	ds_read_b128 v[76:79], v122 offset:8208
	ds_read_b128 v[80:83], v122 offset:12304
	ds_read_b128 v[84:87], v122 offset:16400
	ds_read_b128 v[88:91], v122 offset:20496
	ds_read_b128 v[92:95], v122 offset:24592
	ds_read_b128 v[96:99], v122 offset:28688
	ds_read_b128 v[100:103], v122 offset:32784
	v_fmac_f32_e32 v130, v162, v32
	v_fmac_f32_e32 v131, v162, v36
	v_fmac_f32_e32 v132, v162, v40
	v_fmac_f32_e32 v133, v162, v44
	v_fmac_f32_e32 v134, v162, v48
	v_fmac_f32_e32 v135, v162, v52
	v_fmac_f32_e32 v136, v162, v56
	v_fmac_f32_e32 v137, v162, v60
	v_fmac_f32_e32 v127, v162, v64
	v_fmac_f32_e32 v130, v163, v33
	v_fmac_f32_e32 v131, v163, v37
	v_fmac_f32_e32 v132, v163, v41
	v_fmac_f32_e32 v133, v163, v45
	v_fmac_f32_e32 v134, v163, v49
	v_fmac_f32_e32 v135, v163, v53
	v_fmac_f32_e32 v136, v163, v57
	v_fmac_f32_e32 v137, v163, v61
	v_fmac_f32_e32 v127, v163, v65
	v_fmac_f32_e32 v130, v164, v34
	v_fmac_f32_e32 v131, v164, v38
	v_fmac_f32_e32 v132, v164, v42
	v_fmac_f32_e32 v133, v164, v46
	v_fmac_f32_e32 v134, v164, v50
	v_fmac_f32_e32 v135, v164, v54
	v_fmac_f32_e32 v136, v164, v58
	v_fmac_f32_e32 v137, v164, v62
	v_fmac_f32_e32 v127, v164, v66
	v_fmac_f32_e32 v130, v165, v35
	v_fmac_f32_e32 v131, v165, v39
	v_fmac_f32_e32 v132, v165, v43
	v_fmac_f32_e32 v133, v165, v47
	v_fmac_f32_e32 v134, v165, v51
	v_fmac_f32_e32 v135, v165, v55
	v_fmac_f32_e32 v136, v165, v59
	v_fmac_f32_e32 v137, v165, v63
	v_fmac_f32_e32 v127, v165, v67
	s_waitcnt lgkmcnt(0)
	ds_read_b128 v[32:35], v122 offset:32
	ds_read_b128 v[36:39], v122 offset:4128
	ds_read_b128 v[40:43], v122 offset:8224
	ds_read_b128 v[44:47], v122 offset:12320
	ds_read_b128 v[48:51], v122 offset:16416
	ds_read_b128 v[52:55], v122 offset:20512
	ds_read_b128 v[56:59], v122 offset:24608
	ds_read_b128 v[60:63], v122 offset:28704
	ds_read_b128 v[64:67], v122 offset:32800
	v_fmac_f32_e32 v130, v166, v68
	v_fmac_f32_e32 v131, v166, v72
	v_fmac_f32_e32 v132, v166, v76
	v_fmac_f32_e32 v133, v166, v80
	v_fmac_f32_e32 v134, v166, v84
	v_fmac_f32_e32 v135, v166, v88
	v_fmac_f32_e32 v136, v166, v92
	v_fmac_f32_e32 v137, v166, v96
	v_mul_f32_e32 v104, v166, v100
	v_add_f32_e32 v127, v127, v104
	v_fmac_f32_e32 v130, v167, v69
	v_fmac_f32_e32 v131, v167, v73
	v_fmac_f32_e32 v132, v167, v77
	v_fmac_f32_e32 v133, v167, v81
	v_fmac_f32_e32 v134, v167, v85
	v_fmac_f32_e32 v135, v167, v89
	v_fmac_f32_e32 v136, v167, v93
	v_fmac_f32_e32 v137, v167, v97
	v_mul_f32_e32 v104, v167, v101
	v_add_f32_e32 v127, v127, v104
	v_fmac_f32_e32 v130, v168, v70
	v_fmac_f32_e32 v131, v168, v74
	v_fmac_f32_e32 v132, v168, v78
	v_fmac_f32_e32 v133, v168, v82
	v_fmac_f32_e32 v134, v168, v86
	v_fmac_f32_e32 v135, v168, v90
	v_fmac_f32_e32 v136, v168, v94
	v_fmac_f32_e32 v137, v168, v98
	v_mul_f32_e32 v104, v168, v102
	v_add_f32_e32 v127, v127, v104
	v_fmac_f32_e32 v130, v169, v71
	v_fmac_f32_e32 v131, v169, v75
	v_fmac_f32_e32 v132, v169, v79
	v_fmac_f32_e32 v133, v169, v83
	v_fmac_f32_e32 v134, v169, v87
	v_fmac_f32_e32 v135, v169, v91
	v_fmac_f32_e32 v136, v169, v95
	v_fmac_f32_e32 v137, v169, v99
	v_mul_f32_e32 v104, v169, v103
	v_add_f32_e32 v127, v127, v104
	s_waitcnt lgkmcnt(0)
; __device__ __forceinline__ void phase0(int wv, const Params& p, LAS unsigned char* lds, int cb_first, int cb_stride, int cb_lo, int cb_hi, bool do_rope) {
;     ...
;         for (int k0 = 0; k0 < 128; k0 += 16) { float wq[16];
; #pragma unroll
;             for (int u = 0; u < 16; ++u) wq[u] = w[(size_t)(k0 + u) * 6144];
; #pragma unroll
;             for (int u = 0; u < 16; ++u)
; #pragma unroll
;                 for (int i = 0; i < 9; ++i) acc[i] += sc[i * 1024 + ks * 128 + k0 + u] * wq[u]; }
	ds_read_b128 v[68:71], v122 offset:48
	ds_read_b128 v[72:75], v122 offset:4144
	ds_read_b128 v[76:79], v122 offset:8240
	ds_read_b128 v[80:83], v122 offset:12336
	ds_read_b128 v[84:87], v122 offset:16432
	ds_read_b128 v[88:91], v122 offset:20528
	ds_read_b128 v[92:95], v122 offset:24624
	ds_read_b128 v[96:99], v122 offset:28720
	ds_read_b128 v[100:103], v122 offset:32816
	v_fmac_f32_e32 v130, v170, v32
	v_fmac_f32_e32 v131, v170, v36
	v_fmac_f32_e32 v132, v170, v40
	v_fmac_f32_e32 v133, v170, v44
	v_fmac_f32_e32 v134, v170, v48
	v_fmac_f32_e32 v135, v170, v52
	v_fmac_f32_e32 v136, v170, v56
	v_fmac_f32_e32 v137, v170, v60
	v_mul_f32_e32 v104, v170, v64
	v_add_f32_e32 v127, v127, v104
	v_fmac_f32_e32 v130, v171, v33
	v_fmac_f32_e32 v131, v171, v37
	v_fmac_f32_e32 v132, v171, v41
	v_fmac_f32_e32 v133, v171, v45
	v_fmac_f32_e32 v134, v171, v49
	v_fmac_f32_e32 v135, v171, v53
	v_fmac_f32_e32 v136, v171, v57
	v_fmac_f32_e32 v137, v171, v61
	v_mul_f32_e32 v104, v171, v65
	v_add_f32_e32 v127, v127, v104
	v_fmac_f32_e32 v130, v172, v34
	v_fmac_f32_e32 v131, v172, v38
	v_fmac_f32_e32 v132, v172, v42
	v_fmac_f32_e32 v133, v172, v46
	v_fmac_f32_e32 v134, v172, v50
	v_fmac_f32_e32 v135, v172, v54
	v_fmac_f32_e32 v136, v172, v58
	v_fmac_f32_e32 v137, v172, v62
	v_mul_f32_e32 v104, v172, v66
	v_add_f32_e32 v127, v127, v104
	v_fmac_f32_e32 v130, v173, v35
	v_fmac_f32_e32 v131, v173, v39
	v_fmac_f32_e32 v132, v173, v43
	v_fmac_f32_e32 v133, v173, v47
	v_fmac_f32_e32 v134, v173, v51
	v_fmac_f32_e32 v135, v173, v55
	v_fmac_f32_e32 v136, v173, v59
	v_fmac_f32_e32 v137, v173, v63
	v_mul_f32_e32 v104, v173, v67
	v_add_f32_e32 v127, v127, v104
	s_waitcnt lgkmcnt(0)
	v_fmac_f32_e32 v130, v174, v68
	v_fmac_f32_e32 v131, v174, v72
	v_fmac_f32_e32 v132, v174, v76
	v_fmac_f32_e32 v133, v174, v80
	v_fmac_f32_e32 v134, v174, v84
	v_fmac_f32_e32 v135, v174, v88
	v_fmac_f32_e32 v136, v174, v92
	v_fmac_f32_e32 v137, v174, v96
	v_mul_f32_e32 v104, v174, v100
	v_add_f32_e32 v127, v127, v104
	v_fmac_f32_e32 v130, v175, v69
	v_fmac_f32_e32 v131, v175, v73
	v_fmac_f32_e32 v132, v175, v77
	v_fmac_f32_e32 v133, v175, v81
	v_fmac_f32_e32 v134, v175, v85
	v_fmac_f32_e32 v135, v175, v89
	v_fmac_f32_e32 v136, v175, v93
	v_fmac_f32_e32 v137, v175, v97
	v_mul_f32_e32 v104, v175, v101
	v_add_f32_e32 v127, v127, v104
	v_fmac_f32_e32 v130, v176, v70
	v_fmac_f32_e32 v131, v176, v74
	v_fmac_f32_e32 v132, v176, v78
	v_fmac_f32_e32 v133, v176, v82
	v_fmac_f32_e32 v134, v176, v86
	v_fmac_f32_e32 v135, v176, v90
	v_fmac_f32_e32 v136, v176, v94
	v_fmac_f32_e32 v137, v176, v98
	v_mul_f32_e32 v104, v176, v102
	v_add_f32_e32 v127, v127, v104
	v_fmac_f32_e32 v130, v177, v71
	v_fmac_f32_e32 v131, v177, v75
	v_fmac_f32_e32 v132, v177, v79
	v_fmac_f32_e32 v133, v177, v83
	v_fmac_f32_e32 v134, v177, v87
	v_fmac_f32_e32 v135, v177, v91
	v_fmac_f32_e32 v136, v177, v95
	v_fmac_f32_e32 v137, v177, v99
	v_mul_f32_e32 v104, v177, v103
	v_add_f32_e32 v127, v127, v104
	v_add_u32_e32 v122, 64, v122
	ds_read_b128 v[32:35], v122 offset:0
	ds_read_b128 v[36:39], v122 offset:4096
	ds_read_b128 v[40:43], v122 offset:8192
	ds_read_b128 v[44:47], v122 offset:12288
	ds_read_b128 v[48:51], v122 offset:16384
	ds_read_b128 v[52:55], v122 offset:20480
	ds_read_b128 v[56:59], v122 offset:24576
	ds_read_b128 v[60:63], v122 offset:28672
	ds_read_b128 v[64:67], v122 offset:32768
	s_waitcnt vmcnt(32)
	global_load_dword v162, v[128:129], off
	v_lshl_add_u64 v[128:129], v[128:129], 0, s[18:19]
	global_load_dword v163, v[128:129], off
	v_lshl_add_u64 v[128:129], v[128:129], 0, s[18:19]
	global_load_dword v164, v[128:129], off
	v_lshl_add_u64 v[128:129], v[128:129], 0, s[18:19]
	global_load_dword v165, v[128:129], off
	v_lshl_add_u64 v[128:129], v[128:129], 0, s[18:19]
	global_load_dword v166, v[128:129], off
	v_lshl_add_u64 v[128:129], v[128:129], 0, s[18:19]
	global_load_dword v167, v[128:129], off
	v_lshl_add_u64 v[128:129], v[128:129], 0, s[18:19]
	global_load_dword v168, v[128:129], off
	v_lshl_add_u64 v[128:129], v[128:129], 0, s[18:19]
	global_load_dword v169, v[128:129], off
	v_lshl_add_u64 v[128:129], v[128:129], 0, s[18:19]
	global_load_dword v170, v[128:129], off
	v_lshl_add_u64 v[128:129], v[128:129], 0, s[18:19]
	global_load_dword v171, v[128:129], off
	v_lshl_add_u64 v[128:129], v[128:129], 0, s[18:19]
	global_load_dword v172, v[128:129], off
	v_lshl_add_u64 v[128:129], v[128:129], 0, s[18:19]
	global_load_dword v173, v[128:129], off
	v_lshl_add_u64 v[128:129], v[128:129], 0, s[18:19]
	global_load_dword v174, v[128:129], off
	v_lshl_add_u64 v[128:129], v[128:129], 0, s[18:19]
	global_load_dword v175, v[128:129], off
	v_lshl_add_u64 v[128:129], v[128:129], 0, s[18:19]
	global_load_dword v176, v[128:129], off
	v_lshl_add_u64 v[128:129], v[128:129], 0, s[18:19]
	global_load_dword v177, v[128:129], off
	v_lshl_add_u64 v[128:129], v[128:129], 0, s[18:19]
	s_waitcnt lgkmcnt(0)
	ds_read_b128 v[68:71], v122 offset:16
	ds_read_b128 v[72:75], v122 offset:4112
	ds_read_b128 v[76:79], v122 offset:8208
	ds_read_b128 v[80:83], v122 offset:12304
	ds_read_b128 v[84:87], v122 offset:16400
	ds_read_b128 v[88:91], v122 offset:20496
	ds_read_b128 v[92:95], v122 offset:24592
	ds_read_b128 v[96:99], v122 offset:28688
	ds_read_b128 v[100:103], v122 offset:32784
	v_fmac_f32_e32 v130, v0, v32
	v_fmac_f32_e32 v131, v0, v36
	v_fmac_f32_e32 v132, v0, v40
	v_fmac_f32_e32 v133, v0, v44
	v_fmac_f32_e32 v134, v0, v48
	v_fmac_f32_e32 v135, v0, v52
	v_fmac_f32_e32 v136, v0, v56
	v_fmac_f32_e32 v137, v0, v60
	v_fmac_f32_e32 v127, v0, v64
	v_fmac_f32_e32 v130, v1, v33
	v_fmac_f32_e32 v131, v1, v37
	v_fmac_f32_e32 v132, v1, v41
	v_fmac_f32_e32 v133, v1, v45
	v_fmac_f32_e32 v134, v1, v49
	v_fmac_f32_e32 v135, v1, v53
	v_fmac_f32_e32 v136, v1, v57
	v_fmac_f32_e32 v137, v1, v61
	v_fmac_f32_e32 v127, v1, v65
	v_fmac_f32_e32 v130, v2, v34
	v_fmac_f32_e32 v131, v2, v38
	v_fmac_f32_e32 v132, v2, v42
	v_fmac_f32_e32 v133, v2, v46
	v_fmac_f32_e32 v134, v2, v50
	v_fmac_f32_e32 v135, v2, v54
	v_fmac_f32_e32 v136, v2, v58
	v_fmac_f32_e32 v137, v2, v62
	v_fmac_f32_e32 v127, v2, v66
	v_fmac_f32_e32 v130, v3, v35
	v_fmac_f32_e32 v131, v3, v39
	v_fmac_f32_e32 v132, v3, v43
	v_fmac_f32_e32 v133, v3, v47
	v_fmac_f32_e32 v134, v3, v51
	v_fmac_f32_e32 v135, v3, v55
	v_fmac_f32_e32 v136, v3, v59
	v_fmac_f32_e32 v137, v3, v63
	v_fmac_f32_e32 v127, v3, v67
	s_waitcnt lgkmcnt(0)
; __device__ __forceinline__ void phase0(int wv, const Params& p, LAS unsigned char* lds, int cb_first, int cb_stride, int cb_lo, int cb_hi, bool do_rope) {
;     ...
;         for (int k0 = 0; k0 < 128; k0 += 16) { float wq[16];
; #pragma unroll
;             for (int u = 0; u < 16; ++u) wq[u] = w[(size_t)(k0 + u) * 6144];
; #pragma unroll
;             for (int u = 0; u < 16; ++u)
; #pragma unroll
;                 for (int i = 0; i < 9; ++i) acc[i] += sc[i * 1024 + ks * 128 + k0 + u] * wq[u]; }
	ds_read_b128 v[32:35], v122 offset:32
	ds_read_b128 v[36:39], v122 offset:4128
	ds_read_b128 v[40:43], v122 offset:8224
	ds_read_b128 v[44:47], v122 offset:12320
	ds_read_b128 v[48:51], v122 offset:16416
	ds_read_b128 v[52:55], v122 offset:20512
	ds_read_b128 v[56:59], v122 offset:24608
	ds_read_b128 v[60:63], v122 offset:28704
	ds_read_b128 v[64:67], v122 offset:32800
	v_fmac_f32_e32 v130, v4, v68
	v_fmac_f32_e32 v131, v4, v72
	v_fmac_f32_e32 v132, v4, v76
	v_fmac_f32_e32 v133, v4, v80
	v_fmac_f32_e32 v134, v4, v84
	v_fmac_f32_e32 v135, v4, v88
	v_fmac_f32_e32 v136, v4, v92
	v_fmac_f32_e32 v137, v4, v96
	v_mul_f32_e32 v104, v4, v100
	v_add_f32_e32 v127, v127, v104
	v_fmac_f32_e32 v130, v5, v69
	v_fmac_f32_e32 v131, v5, v73
	v_fmac_f32_e32 v132, v5, v77
	v_fmac_f32_e32 v133, v5, v81
	v_fmac_f32_e32 v134, v5, v85
	v_fmac_f32_e32 v135, v5, v89
	v_fmac_f32_e32 v136, v5, v93
	v_fmac_f32_e32 v137, v5, v97
	v_mul_f32_e32 v104, v5, v101
	v_add_f32_e32 v127, v127, v104
	v_fmac_f32_e32 v130, v6, v70
	v_fmac_f32_e32 v131, v6, v74
	v_fmac_f32_e32 v132, v6, v78
	v_fmac_f32_e32 v133, v6, v82
	v_fmac_f32_e32 v134, v6, v86
	v_fmac_f32_e32 v135, v6, v90
	v_fmac_f32_e32 v136, v6, v94
	v_fmac_f32_e32 v137, v6, v98
	v_mul_f32_e32 v104, v6, v102
	v_add_f32_e32 v127, v127, v104
	v_fmac_f32_e32 v130, v7, v71
	v_fmac_f32_e32 v131, v7, v75
	v_fmac_f32_e32 v132, v7, v79
	v_fmac_f32_e32 v133, v7, v83
	v_fmac_f32_e32 v134, v7, v87
	v_fmac_f32_e32 v135, v7, v91
	v_fmac_f32_e32 v136, v7, v95
	v_fmac_f32_e32 v137, v7, v99
	v_mul_f32_e32 v104, v7, v103
	v_add_f32_e32 v127, v127, v104
	s_waitcnt lgkmcnt(0)
	ds_read_b128 v[68:71], v122 offset:48
	ds_read_b128 v[72:75], v122 offset:4144
	ds_read_b128 v[76:79], v122 offset:8240
	ds_read_b128 v[80:83], v122 offset:12336
	ds_read_b128 v[84:87], v122 offset:16432
	ds_read_b128 v[88:91], v122 offset:20528
	ds_read_b128 v[92:95], v122 offset:24624
	ds_read_b128 v[96:99], v122 offset:28720
	ds_read_b128 v[100:103], v122 offset:32816
	v_fmac_f32_e32 v130, v8, v32
	v_fmac_f32_e32 v131, v8, v36
	v_fmac_f32_e32 v132, v8, v40
	v_fmac_f32_e32 v133, v8, v44
	v_fmac_f32_e32 v134, v8, v48
	v_fmac_f32_e32 v135, v8, v52
	v_fmac_f32_e32 v136, v8, v56
	v_fmac_f32_e32 v137, v8, v60
	v_mul_f32_e32 v104, v8, v64
	v_add_f32_e32 v127, v127, v104
	v_fmac_f32_e32 v130, v9, v33
	v_fmac_f32_e32 v131, v9, v37
	v_fmac_f32_e32 v132, v9, v41
	v_fmac_f32_e32 v133, v9, v45
	v_fmac_f32_e32 v134, v9, v49
	v_fmac_f32_e32 v135, v9, v53
	v_fmac_f32_e32 v136, v9, v57
	v_fmac_f32_e32 v137, v9, v61
	v_mul_f32_e32 v104, v9, v65
	v_add_f32_e32 v127, v127, v104
	v_fmac_f32_e32 v130, v10, v34
	v_fmac_f32_e32 v131, v10, v38
	v_fmac_f32_e32 v132, v10, v42
	v_fmac_f32_e32 v133, v10, v46
	v_fmac_f32_e32 v134, v10, v50
	v_fmac_f32_e32 v135, v10, v54
	v_fmac_f32_e32 v136, v10, v58
	v_fmac_f32_e32 v137, v10, v62
	v_mul_f32_e32 v104, v10, v66
	v_add_f32_e32 v127, v127, v104
	v_fmac_f32_e32 v130, v11, v35
	v_fmac_f32_e32 v131, v11, v39
	v_fmac_f32_e32 v132, v11, v43
	v_fmac_f32_e32 v133, v11, v47
	v_fmac_f32_e32 v134, v11, v51
	v_fmac_f32_e32 v135, v11, v55
	v_fmac_f32_e32 v136, v11, v59
	v_fmac_f32_e32 v137, v11, v63
	v_mul_f32_e32 v104, v11, v67
	v_add_f32_e32 v127, v127, v104
	s_waitcnt lgkmcnt(0)
	v_fmac_f32_e32 v130, v12, v68
	v_fmac_f32_e32 v131, v12, v72
	v_fmac_f32_e32 v132, v12, v76
	v_fmac_f32_e32 v133, v12, v80
	v_fmac_f32_e32 v134, v12, v84
	v_fmac_f32_e32 v135, v12, v88
	v_fmac_f32_e32 v136, v12, v92
	v_fmac_f32_e32 v137, v12, v96
	v_mul_f32_e32 v104, v12, v100
	v_add_f32_e32 v127, v127, v104
	v_fmac_f32_e32 v130, v13, v69
	v_fmac_f32_e32 v131, v13, v73
	v_fmac_f32_e32 v132, v13, v77
	v_fmac_f32_e32 v133, v13, v81
	v_fmac_f32_e32 v134, v13, v85
	v_fmac_f32_e32 v135, v13, v89
	v_fmac_f32_e32 v136, v13, v93
	v_fmac_f32_e32 v137, v13, v97
	v_mul_f32_e32 v104, v13, v101
	v_add_f32_e32 v127, v127, v104
	v_fmac_f32_e32 v130, v14, v70
	v_fmac_f32_e32 v131, v14, v74
	v_fmac_f32_e32 v132, v14, v78
	v_fmac_f32_e32 v133, v14, v82
	v_fmac_f32_e32 v134, v14, v86
	v_fmac_f32_e32 v135, v14, v90
	v_fmac_f32_e32 v136, v14, v94
	v_fmac_f32_e32 v137, v14, v98
	v_mul_f32_e32 v104, v14, v102
	v_add_f32_e32 v127, v127, v104
	v_fmac_f32_e32 v130, v15, v71
	v_fmac_f32_e32 v131, v15, v75
	v_fmac_f32_e32 v132, v15, v79
	v_fmac_f32_e32 v133, v15, v83
	v_fmac_f32_e32 v134, v15, v87
	v_fmac_f32_e32 v135, v15, v91
	v_fmac_f32_e32 v136, v15, v95
	v_fmac_f32_e32 v137, v15, v99
	v_mul_f32_e32 v104, v15, v103
	v_add_f32_e32 v127, v127, v104
	v_add_u32_e32 v122, 64, v122
	ds_read_b128 v[32:35], v122 offset:0
	ds_read_b128 v[36:39], v122 offset:4096
	ds_read_b128 v[40:43], v122 offset:8192
	ds_read_b128 v[44:47], v122 offset:12288
	ds_read_b128 v[48:51], v122 offset:16384
	ds_read_b128 v[52:55], v122 offset:20480
	ds_read_b128 v[56:59], v122 offset:24576
	ds_read_b128 v[60:63], v122 offset:28672
	ds_read_b128 v[64:67], v122 offset:32768
	s_waitcnt vmcnt(32)
	s_waitcnt lgkmcnt(0)
; __device__ __forceinline__ void phase0(int wv, const Params& p, LAS unsigned char* lds, int cb_first, int cb_stride, int cb_lo, int cb_hi, bool do_rope) {
;     ...
;         for (int k0 = 0; k0 < 128; k0 += 16) { float wq[16];
; #pragma unroll
;             for (int u = 0; u < 16; ++u) wq[u] = w[(size_t)(k0 + u) * 6144];
; #pragma unroll
;             for (int u = 0; u < 16; ++u)
; #pragma unroll
;                 for (int i = 0; i < 9; ++i) acc[i] += sc[i * 1024 + ks * 128 + k0 + u] * wq[u]; }
	ds_read_b128 v[68:71], v122 offset:16
	ds_read_b128 v[72:75], v122 offset:4112
	ds_read_b128 v[76:79], v122 offset:8208
	ds_read_b128 v[80:83], v122 offset:12304
	ds_read_b128 v[84:87], v122 offset:16400
	ds_read_b128 v[88:91], v122 offset:20496
	ds_read_b128 v[92:95], v122 offset:24592
	ds_read_b128 v[96:99], v122 offset:28688
	ds_read_b128 v[100:103], v122 offset:32784
	v_fmac_f32_e32 v130, v16, v32
	v_fmac_f32_e32 v131, v16, v36
	v_fmac_f32_e32 v132, v16, v40
	v_fmac_f32_e32 v133, v16, v44
	v_fmac_f32_e32 v134, v16, v48
	v_fmac_f32_e32 v135, v16, v52
	v_fmac_f32_e32 v136, v16, v56
	v_fmac_f32_e32 v137, v16, v60
	v_fmac_f32_e32 v127, v16, v64
	v_fmac_f32_e32 v130, v17, v33
	v_fmac_f32_e32 v131, v17, v37
	v_fmac_f32_e32 v132, v17, v41
	v_fmac_f32_e32 v133, v17, v45
	v_fmac_f32_e32 v134, v17, v49
	v_fmac_f32_e32 v135, v17, v53
	v_fmac_f32_e32 v136, v17, v57
	v_fmac_f32_e32 v137, v17, v61
	v_fmac_f32_e32 v127, v17, v65
	v_fmac_f32_e32 v130, v18, v34
	v_fmac_f32_e32 v131, v18, v38
	v_fmac_f32_e32 v132, v18, v42
	v_fmac_f32_e32 v133, v18, v46
	v_fmac_f32_e32 v134, v18, v50
	v_fmac_f32_e32 v135, v18, v54
	v_fmac_f32_e32 v136, v18, v58
	v_fmac_f32_e32 v137, v18, v62
	v_fmac_f32_e32 v127, v18, v66
	v_fmac_f32_e32 v130, v19, v35
	v_fmac_f32_e32 v131, v19, v39
	v_fmac_f32_e32 v132, v19, v43
	v_fmac_f32_e32 v133, v19, v47
	v_fmac_f32_e32 v134, v19, v51
	v_fmac_f32_e32 v135, v19, v55
	v_fmac_f32_e32 v136, v19, v59
	v_fmac_f32_e32 v137, v19, v63
	v_fmac_f32_e32 v127, v19, v67
	s_waitcnt lgkmcnt(0)
	ds_read_b128 v[32:35], v122 offset:32
	ds_read_b128 v[36:39], v122 offset:4128
	ds_read_b128 v[40:43], v122 offset:8224
	ds_read_b128 v[44:47], v122 offset:12320
	ds_read_b128 v[48:51], v122 offset:16416
	ds_read_b128 v[52:55], v122 offset:20512
	ds_read_b128 v[56:59], v122 offset:24608
	ds_read_b128 v[60:63], v122 offset:28704
	ds_read_b128 v[64:67], v122 offset:32800
	v_fmac_f32_e32 v130, v20, v68
	v_fmac_f32_e32 v131, v20, v72
	v_fmac_f32_e32 v132, v20, v76
	v_fmac_f32_e32 v133, v20, v80
	v_fmac_f32_e32 v134, v20, v84
	v_fmac_f32_e32 v135, v20, v88
	v_fmac_f32_e32 v136, v20, v92
	v_fmac_f32_e32 v137, v20, v96
	v_mul_f32_e32 v104, v20, v100
	v_add_f32_e32 v127, v127, v104
	v_fmac_f32_e32 v130, v21, v69
	v_fmac_f32_e32 v131, v21, v73
	v_fmac_f32_e32 v132, v21, v77
	v_fmac_f32_e32 v133, v21, v81
	v_fmac_f32_e32 v134, v21, v85
	v_fmac_f32_e32 v135, v21, v89
	v_fmac_f32_e32 v136, v21, v93
	v_fmac_f32_e32 v137, v21, v97
	v_mul_f32_e32 v104, v21, v101
	v_add_f32_e32 v127, v127, v104
	v_fmac_f32_e32 v130, v22, v70
	v_fmac_f32_e32 v131, v22, v74
	v_fmac_f32_e32 v132, v22, v78
	v_fmac_f32_e32 v133, v22, v82
	v_fmac_f32_e32 v134, v22, v86
	v_fmac_f32_e32 v135, v22, v90
	v_fmac_f32_e32 v136, v22, v94
	v_fmac_f32_e32 v137, v22, v98
	v_mul_f32_e32 v104, v22, v102
	v_add_f32_e32 v127, v127, v104
	v_fmac_f32_e32 v130, v23, v71
	v_fmac_f32_e32 v131, v23, v75
	v_fmac_f32_e32 v132, v23, v79
	v_fmac_f32_e32 v133, v23, v83
	v_fmac_f32_e32 v134, v23, v87
	v_fmac_f32_e32 v135, v23, v91
	v_fmac_f32_e32 v136, v23, v95
	v_fmac_f32_e32 v137, v23, v99
	v_mul_f32_e32 v104, v23, v103
	v_add_f32_e32 v127, v127, v104
	s_waitcnt lgkmcnt(0)
	ds_read_b128 v[68:71], v122 offset:48
	ds_read_b128 v[72:75], v122 offset:4144
	ds_read_b128 v[76:79], v122 offset:8240
	ds_read_b128 v[80:83], v122 offset:12336
	ds_read_b128 v[84:87], v122 offset:16432
	ds_read_b128 v[88:91], v122 offset:20528
	ds_read_b128 v[92:95], v122 offset:24624
	ds_read_b128 v[96:99], v122 offset:28720
	ds_read_b128 v[100:103], v122 offset:32816
	v_fmac_f32_e32 v130, v24, v32
	v_fmac_f32_e32 v131, v24, v36
	v_fmac_f32_e32 v132, v24, v40
	v_fmac_f32_e32 v133, v24, v44
	v_fmac_f32_e32 v134, v24, v48
	v_fmac_f32_e32 v135, v24, v52
	v_fmac_f32_e32 v136, v24, v56
	v_fmac_f32_e32 v137, v24, v60
	v_mul_f32_e32 v104, v24, v64
	v_add_f32_e32 v127, v127, v104
	v_fmac_f32_e32 v130, v25, v33
	v_fmac_f32_e32 v131, v25, v37
	v_fmac_f32_e32 v132, v25, v41
	v_fmac_f32_e32 v133, v25, v45
	v_fmac_f32_e32 v134, v25, v49
	v_fmac_f32_e32 v135, v25, v53
	v_fmac_f32_e32 v136, v25, v57
	v_fmac_f32_e32 v137, v25, v61
	v_mul_f32_e32 v104, v25, v65
	v_add_f32_e32 v127, v127, v104
	v_fmac_f32_e32 v130, v26, v34
	v_fmac_f32_e32 v131, v26, v38
	v_fmac_f32_e32 v132, v26, v42
	v_fmac_f32_e32 v133, v26, v46
	v_fmac_f32_e32 v134, v26, v50
	v_fmac_f32_e32 v135, v26, v54
	v_fmac_f32_e32 v136, v26, v58
	v_fmac_f32_e32 v137, v26, v62
	v_mul_f32_e32 v104, v26, v66
	v_add_f32_e32 v127, v127, v104
	v_fmac_f32_e32 v130, v27, v35
	v_fmac_f32_e32 v131, v27, v39
	v_fmac_f32_e32 v132, v27, v43
	v_fmac_f32_e32 v133, v27, v47
	v_fmac_f32_e32 v134, v27, v51
	v_fmac_f32_e32 v135, v27, v55
	v_fmac_f32_e32 v136, v27, v59
	v_fmac_f32_e32 v137, v27, v63
	v_mul_f32_e32 v104, v27, v67
	v_add_f32_e32 v127, v127, v104
	s_waitcnt lgkmcnt(0)
	v_fmac_f32_e32 v130, v28, v68
	v_fmac_f32_e32 v131, v28, v72
	v_fmac_f32_e32 v132, v28, v76
	v_fmac_f32_e32 v133, v28, v80
	v_fmac_f32_e32 v134, v28, v84
	v_fmac_f32_e32 v135, v28, v88
	v_fmac_f32_e32 v136, v28, v92
	v_fmac_f32_e32 v137, v28, v96
	v_mul_f32_e32 v104, v28, v100
	v_add_f32_e32 v127, v127, v104
	v_fmac_f32_e32 v130, v29, v69
	v_fmac_f32_e32 v131, v29, v73
	v_fmac_f32_e32 v132, v29, v77
	v_fmac_f32_e32 v133, v29, v81
	v_fmac_f32_e32 v134, v29, v85
	v_fmac_f32_e32 v135, v29, v89
	v_fmac_f32_e32 v136, v29, v93
	v_fmac_f32_e32 v137, v29, v97
	v_mul_f32_e32 v104, v29, v101
	v_add_f32_e32 v127, v127, v104
	v_fmac_f32_e32 v130, v30, v70
	v_fmac_f32_e32 v131, v30, v74
	v_fmac_f32_e32 v132, v30, v78
	v_fmac_f32_e32 v133, v30, v82
	v_fmac_f32_e32 v134, v30, v86
	v_fmac_f32_e32 v135, v30, v90
	v_fmac_f32_e32 v136, v30, v94
	v_fmac_f32_e32 v137, v30, v98
	v_mul_f32_e32 v104, v30, v102
	v_add_f32_e32 v127, v127, v104
	v_fmac_f32_e32 v130, v31, v71
	v_fmac_f32_e32 v131, v31, v75
	v_fmac_f32_e32 v132, v31, v79
	v_fmac_f32_e32 v133, v31, v83
	v_fmac_f32_e32 v134, v31, v87
	v_fmac_f32_e32 v135, v31, v91
	v_fmac_f32_e32 v136, v31, v95
	v_fmac_f32_e32 v137, v31, v99
	v_mul_f32_e32 v104, v31, v103
	v_add_f32_e32 v127, v127, v104
	v_add_u32_e32 v122, 64, v122
	ds_read_b128 v[32:35], v122 offset:0
	ds_read_b128 v[36:39], v122 offset:4096
	ds_read_b128 v[40:43], v122 offset:8192
	ds_read_b128 v[44:47], v122 offset:12288
	ds_read_b128 v[48:51], v122 offset:16384
	ds_read_b128 v[52:55], v122 offset:20480
	ds_read_b128 v[56:59], v122 offset:24576
	ds_read_b128 v[60:63], v122 offset:28672
	ds_read_b128 v[64:67], v122 offset:32768
	s_waitcnt vmcnt(16)
; __device__ __forceinline__ void phase0(int wv, const Params& p, LAS unsigned char* lds, int cb_first, int cb_stride, int cb_lo, int cb_hi, bool do_rope) {
;     ...
;         for (int k0 = 0; k0 < 128; k0 += 16) { float wq[16];
; #pragma unroll
;             for (int u = 0; u < 16; ++u) wq[u] = w[(size_t)(k0 + u) * 6144];
; #pragma unroll
;             for (int u = 0; u < 16; ++u)
; #pragma unroll
;                 for (int i = 0; i < 9; ++i) acc[i] += sc[i * 1024 + ks * 128 + k0 + u] * wq[u]; }
	s_waitcnt lgkmcnt(0)
	ds_read_b128 v[68:71], v122 offset:16
	ds_read_b128 v[72:75], v122 offset:4112
	ds_read_b128 v[76:79], v122 offset:8208
	ds_read_b128 v[80:83], v122 offset:12304
	ds_read_b128 v[84:87], v122 offset:16400
	ds_read_b128 v[88:91], v122 offset:20496
	ds_read_b128 v[92:95], v122 offset:24592
	ds_read_b128 v[96:99], v122 offset:28688
	ds_read_b128 v[100:103], v122 offset:32784
	v_fmac_f32_e32 v130, v146, v32
	v_fmac_f32_e32 v131, v146, v36
	v_fmac_f32_e32 v132, v146, v40
	v_fmac_f32_e32 v133, v146, v44
	v_fmac_f32_e32 v134, v146, v48
	v_fmac_f32_e32 v135, v146, v52
	v_fmac_f32_e32 v136, v146, v56
	v_fmac_f32_e32 v137, v146, v60
	v_fmac_f32_e32 v127, v146, v64
	v_fmac_f32_e32 v130, v147, v33
	v_fmac_f32_e32 v131, v147, v37
	v_fmac_f32_e32 v132, v147, v41
	v_fmac_f32_e32 v133, v147, v45
	v_fmac_f32_e32 v134, v147, v49
	v_fmac_f32_e32 v135, v147, v53
	v_fmac_f32_e32 v136, v147, v57
	v_fmac_f32_e32 v137, v147, v61
	v_fmac_f32_e32 v127, v147, v65
	v_fmac_f32_e32 v130, v148, v34
	v_fmac_f32_e32 v131, v148, v38
	v_fmac_f32_e32 v132, v148, v42
	v_fmac_f32_e32 v133, v148, v46
	v_fmac_f32_e32 v134, v148, v50
	v_fmac_f32_e32 v135, v148, v54
	v_fmac_f32_e32 v136, v148, v58
	v_fmac_f32_e32 v137, v148, v62
	v_fmac_f32_e32 v127, v148, v66
	v_fmac_f32_e32 v130, v149, v35
	v_fmac_f32_e32 v131, v149, v39
	v_fmac_f32_e32 v132, v149, v43
	v_fmac_f32_e32 v133, v149, v47
	v_fmac_f32_e32 v134, v149, v51
	v_fmac_f32_e32 v135, v149, v55
	v_fmac_f32_e32 v136, v149, v59
	v_fmac_f32_e32 v137, v149, v63
	v_fmac_f32_e32 v127, v149, v67
	s_waitcnt lgkmcnt(0)
	ds_read_b128 v[32:35], v122 offset:32
	ds_read_b128 v[36:39], v122 offset:4128
	ds_read_b128 v[40:43], v122 offset:8224
	ds_read_b128 v[44:47], v122 offset:12320
	ds_read_b128 v[48:51], v122 offset:16416
	ds_read_b128 v[52:55], v122 offset:20512
	ds_read_b128 v[56:59], v122 offset:24608
	ds_read_b128 v[60:63], v122 offset:28704
	ds_read_b128 v[64:67], v122 offset:32800
	v_fmac_f32_e32 v130, v150, v68
	v_fmac_f32_e32 v131, v150, v72
	v_fmac_f32_e32 v132, v150, v76
	v_fmac_f32_e32 v133, v150, v80
	v_fmac_f32_e32 v134, v150, v84
	v_fmac_f32_e32 v135, v150, v88
	v_fmac_f32_e32 v136, v150, v92
	v_fmac_f32_e32 v137, v150, v96
	v_mul_f32_e32 v104, v150, v100
	v_add_f32_e32 v127, v127, v104
	v_fmac_f32_e32 v130, v151, v69
	v_fmac_f32_e32 v131, v151, v73
	v_fmac_f32_e32 v132, v151, v77
	v_fmac_f32_e32 v133, v151, v81
	v_fmac_f32_e32 v134, v151, v85
	v_fmac_f32_e32 v135, v151, v89
	v_fmac_f32_e32 v136, v151, v93
	v_fmac_f32_e32 v137, v151, v97
	v_mul_f32_e32 v104, v151, v101
	v_add_f32_e32 v127, v127, v104
	v_fmac_f32_e32 v130, v152, v70
	v_fmac_f32_e32 v131, v152, v74
	v_fmac_f32_e32 v132, v152, v78
	v_fmac_f32_e32 v133, v152, v82
	v_fmac_f32_e32 v134, v152, v86
	v_fmac_f32_e32 v135, v152, v90
	v_fmac_f32_e32 v136, v152, v94
	v_fmac_f32_e32 v137, v152, v98
	v_mul_f32_e32 v104, v152, v102
	v_add_f32_e32 v127, v127, v104
	v_fmac_f32_e32 v130, v153, v71
	v_fmac_f32_e32 v131, v153, v75
	v_fmac_f32_e32 v132, v153, v79
	v_fmac_f32_e32 v133, v153, v83
	v_fmac_f32_e32 v134, v153, v87
	v_fmac_f32_e32 v135, v153, v91
	v_fmac_f32_e32 v136, v153, v95
	v_fmac_f32_e32 v137, v153, v99
	v_mul_f32_e32 v104, v153, v103
	v_add_f32_e32 v127, v127, v104
	s_waitcnt lgkmcnt(0)
	ds_read_b128 v[68:71], v122 offset:48
	ds_read_b128 v[72:75], v122 offset:4144
	ds_read_b128 v[76:79], v122 offset:8240
	ds_read_b128 v[80:83], v122 offset:12336
	ds_read_b128 v[84:87], v122 offset:16432
	ds_read_b128 v[88:91], v122 offset:20528
	ds_read_b128 v[92:95], v122 offset:24624
	ds_read_b128 v[96:99], v122 offset:28720
	ds_read_b128 v[100:103], v122 offset:32816
	v_fmac_f32_e32 v130, v154, v32
	v_fmac_f32_e32 v131, v154, v36
	v_fmac_f32_e32 v132, v154, v40
	v_fmac_f32_e32 v133, v154, v44
	v_fmac_f32_e32 v134, v154, v48
	v_fmac_f32_e32 v135, v154, v52
	v_fmac_f32_e32 v136, v154, v56
	v_fmac_f32_e32 v137, v154, v60
	v_mul_f32_e32 v104, v154, v64
	v_add_f32_e32 v127, v127, v104
	v_fmac_f32_e32 v130, v155, v33
	v_fmac_f32_e32 v131, v155, v37
	v_fmac_f32_e32 v132, v155, v41
	v_fmac_f32_e32 v133, v155, v45
	v_fmac_f32_e32 v134, v155, v49
	v_fmac_f32_e32 v135, v155, v53
	v_fmac_f32_e32 v136, v155, v57
	v_fmac_f32_e32 v137, v155, v61
	v_mul_f32_e32 v104, v155, v65
	v_add_f32_e32 v127, v127, v104
	v_fmac_f32_e32 v130, v156, v34
	v_fmac_f32_e32 v131, v156, v38
	v_fmac_f32_e32 v132, v156, v42
	v_fmac_f32_e32 v133, v156, v46
	v_fmac_f32_e32 v134, v156, v50
	v_fmac_f32_e32 v135, v156, v54
	v_fmac_f32_e32 v136, v156, v58
	v_fmac_f32_e32 v137, v156, v62
	v_mul_f32_e32 v104, v156, v66
	v_add_f32_e32 v127, v127, v104
	v_fmac_f32_e32 v130, v157, v35
	v_fmac_f32_e32 v131, v157, v39
	v_fmac_f32_e32 v132, v157, v43
	v_fmac_f32_e32 v133, v157, v47
	v_fmac_f32_e32 v134, v157, v51
	v_fmac_f32_e32 v135, v157, v55
	v_fmac_f32_e32 v136, v157, v59
	v_fmac_f32_e32 v137, v157, v63
	v_mul_f32_e32 v104, v157, v67
	v_add_f32_e32 v127, v127, v104
	s_waitcnt lgkmcnt(0)
; __device__ __forceinline__ void phase0(int wv, const Params& p, LAS unsigned char* lds, int cb_first, int cb_stride, int cb_lo, int cb_hi, bool do_rope) {
;     ...
;         for (int k0 = 0; k0 < 128; k0 += 16) { float wq[16];
; #pragma unroll
;             for (int u = 0; u < 16; ++u) wq[u] = w[(size_t)(k0 + u) * 6144];
; #pragma unroll
;             for (int u = 0; u < 16; ++u)
; #pragma unroll
;                 for (int i = 0; i < 9; ++i) acc[i] += sc[i * 1024 + ks * 128 + k0 + u] * wq[u]; }
	v_fmac_f32_e32 v130, v158, v68
	v_fmac_f32_e32 v131, v158, v72
	v_fmac_f32_e32 v132, v158, v76
	v_fmac_f32_e32 v133, v158, v80
	v_fmac_f32_e32 v134, v158, v84
	v_fmac_f32_e32 v135, v158, v88
	v_fmac_f32_e32 v136, v158, v92
	v_fmac_f32_e32 v137, v158, v96
	v_mul_f32_e32 v104, v158, v100
	v_add_f32_e32 v127, v127, v104
	v_fmac_f32_e32 v130, v159, v69
	v_fmac_f32_e32 v131, v159, v73
	v_fmac_f32_e32 v132, v159, v77
	v_fmac_f32_e32 v133, v159, v81
	v_fmac_f32_e32 v134, v159, v85
	v_fmac_f32_e32 v135, v159, v89
	v_fmac_f32_e32 v136, v159, v93
	v_fmac_f32_e32 v137, v159, v97
	v_mul_f32_e32 v104, v159, v101
	v_add_f32_e32 v127, v127, v104
	v_fmac_f32_e32 v130, v160, v70
	v_fmac_f32_e32 v131, v160, v74
	v_fmac_f32_e32 v132, v160, v78
	v_fmac_f32_e32 v133, v160, v82
	v_fmac_f32_e32 v134, v160, v86
	v_fmac_f32_e32 v135, v160, v90
	v_fmac_f32_e32 v136, v160, v94
	v_fmac_f32_e32 v137, v160, v98
	v_mul_f32_e32 v104, v160, v102
	v_add_f32_e32 v127, v127, v104
	v_fmac_f32_e32 v130, v161, v71
	v_fmac_f32_e32 v131, v161, v75
	v_fmac_f32_e32 v132, v161, v79
	v_fmac_f32_e32 v133, v161, v83
	v_fmac_f32_e32 v134, v161, v87
	v_fmac_f32_e32 v135, v161, v91
	v_fmac_f32_e32 v136, v161, v95
	v_fmac_f32_e32 v137, v161, v99
	v_mul_f32_e32 v104, v161, v103
	v_add_f32_e32 v127, v127, v104
	v_add_u32_e32 v122, 64, v122
	ds_read_b128 v[32:35], v122 offset:0
	ds_read_b128 v[36:39], v122 offset:4096
	ds_read_b128 v[40:43], v122 offset:8192
	ds_read_b128 v[44:47], v122 offset:12288
	ds_read_b128 v[48:51], v122 offset:16384
	ds_read_b128 v[52:55], v122 offset:20480
	ds_read_b128 v[56:59], v122 offset:24576
	ds_read_b128 v[60:63], v122 offset:28672
	ds_read_b128 v[64:67], v122 offset:32768
	s_waitcnt vmcnt(0)
	s_waitcnt lgkmcnt(0)
	ds_read_b128 v[68:71], v122 offset:16
	ds_read_b128 v[72:75], v122 offset:4112
	ds_read_b128 v[76:79], v122 offset:8208
	ds_read_b128 v[80:83], v122 offset:12304
	ds_read_b128 v[84:87], v122 offset:16400
	ds_read_b128 v[88:91], v122 offset:20496
	ds_read_b128 v[92:95], v122 offset:24592
	ds_read_b128 v[96:99], v122 offset:28688
	ds_read_b128 v[100:103], v122 offset:32784
	v_fmac_f32_e32 v130, v162, v32
	v_fmac_f32_e32 v131, v162, v36
	v_fmac_f32_e32 v132, v162, v40
	v_fmac_f32_e32 v133, v162, v44
	v_fmac_f32_e32 v134, v162, v48
	v_fmac_f32_e32 v135, v162, v52
	v_fmac_f32_e32 v136, v162, v56
	v_fmac_f32_e32 v137, v162, v60
	v_fmac_f32_e32 v127, v162, v64
	v_fmac_f32_e32 v130, v163, v33
	v_fmac_f32_e32 v131, v163, v37
	v_fmac_f32_e32 v132, v163, v41
	v_fmac_f32_e32 v133, v163, v45
	v_fmac_f32_e32 v134, v163, v49
	v_fmac_f32_e32 v135, v163, v53
	v_fmac_f32_e32 v136, v163, v57
	v_fmac_f32_e32 v137, v163, v61
	v_fmac_f32_e32 v127, v163, v65
	v_fmac_f32_e32 v130, v164, v34
	v_fmac_f32_e32 v131, v164, v38
	v_fmac_f32_e32 v132, v164, v42
	v_fmac_f32_e32 v133, v164, v46
	v_fmac_f32_e32 v134, v164, v50
	v_fmac_f32_e32 v135, v164, v54
	v_fmac_f32_e32 v136, v164, v58
	v_fmac_f32_e32 v137, v164, v62
	v_fmac_f32_e32 v127, v164, v66
	v_fmac_f32_e32 v130, v165, v35
	v_fmac_f32_e32 v131, v165, v39
	v_fmac_f32_e32 v132, v165, v43
	v_fmac_f32_e32 v133, v165, v47
	v_fmac_f32_e32 v134, v165, v51
	v_fmac_f32_e32 v135, v165, v55
	v_fmac_f32_e32 v136, v165, v59
	v_fmac_f32_e32 v137, v165, v63
	v_fmac_f32_e32 v127, v165, v67
	s_waitcnt lgkmcnt(0)
	ds_read_b128 v[32:35], v122 offset:32
	ds_read_b128 v[36:39], v122 offset:4128
	ds_read_b128 v[40:43], v122 offset:8224
	ds_read_b128 v[44:47], v122 offset:12320
	ds_read_b128 v[48:51], v122 offset:16416
	ds_read_b128 v[52:55], v122 offset:20512
	ds_read_b128 v[56:59], v122 offset:24608
	ds_read_b128 v[60:63], v122 offset:28704
	ds_read_b128 v[64:67], v122 offset:32800
	v_fmac_f32_e32 v130, v166, v68
	v_fmac_f32_e32 v131, v166, v72
	v_fmac_f32_e32 v132, v166, v76
	v_fmac_f32_e32 v133, v166, v80
	v_fmac_f32_e32 v134, v166, v84
	v_fmac_f32_e32 v135, v166, v88
	v_fmac_f32_e32 v136, v166, v92
	v_fmac_f32_e32 v137, v166, v96
	v_mul_f32_e32 v104, v166, v100
	v_add_f32_e32 v127, v127, v104
	v_fmac_f32_e32 v130, v167, v69
	v_fmac_f32_e32 v131, v167, v73
	v_fmac_f32_e32 v132, v167, v77
	v_fmac_f32_e32 v133, v167, v81
	v_fmac_f32_e32 v134, v167, v85
	v_fmac_f32_e32 v135, v167, v89
	v_fmac_f32_e32 v136, v167, v93
	v_fmac_f32_e32 v137, v167, v97
	v_mul_f32_e32 v104, v167, v101
	v_add_f32_e32 v127, v127, v104
	v_fmac_f32_e32 v130, v168, v70
	v_fmac_f32_e32 v131, v168, v74
	v_fmac_f32_e32 v132, v168, v78
	v_fmac_f32_e32 v133, v168, v82
	v_fmac_f32_e32 v134, v168, v86
	v_fmac_f32_e32 v135, v168, v90
	v_fmac_f32_e32 v136, v168, v94
	v_fmac_f32_e32 v137, v168, v98
	v_mul_f32_e32 v104, v168, v102
	v_add_f32_e32 v127, v127, v104
	v_fmac_f32_e32 v130, v169, v71
	v_fmac_f32_e32 v131, v169, v75
	v_fmac_f32_e32 v132, v169, v79
	v_fmac_f32_e32 v133, v169, v83
	v_fmac_f32_e32 v134, v169, v87
	v_fmac_f32_e32 v135, v169, v91
	v_fmac_f32_e32 v136, v169, v95
	v_fmac_f32_e32 v137, v169, v99
	v_mul_f32_e32 v104, v169, v103
	v_add_f32_e32 v127, v127, v104
	s_waitcnt lgkmcnt(0)
; __device__ __forceinline__ void phase0(int wv, const Params& p, LAS unsigned char* lds, int cb_first, int cb_stride, int cb_lo, int cb_hi, bool do_rope) {
;     ...
;             for (int u = 0; u < 16; ++u)
; #pragma unroll
;                 for (int i = 0; i < 9; ++i) acc[i] += sc[i * 1024 + ks * 128 + k0 + u] * wq[u]; }
; #pragma unroll
;         for (int i = 0; i < 9; ++i) part[(ks * 9 + i) * 64 + nl] = acc[i];
;         __syncthreads();
;         for (int e = tid; e < 576; e += 512) { const int i = e >> 6, nn = e & 63; float s = 0.f;
; #pragma unroll
;             for (int k2 = 0; k2 < 8; ++k2) s += part[(k2 * 9 + i) * 64 + nn];
;             mod[((size_t)l * 9 + i) * 6144 + nb * 64 + nn] = s + p.ada_b[l * 6144 + nb * 64 + nn]; }
	ds_read_b128 v[68:71], v122 offset:48
	ds_read_b128 v[72:75], v122 offset:4144
	ds_read_b128 v[76:79], v122 offset:8240
	ds_read_b128 v[80:83], v122 offset:12336
	ds_read_b128 v[84:87], v122 offset:16432
	ds_read_b128 v[88:91], v122 offset:20528
	ds_read_b128 v[92:95], v122 offset:24624
	ds_read_b128 v[96:99], v122 offset:28720
	ds_read_b128 v[100:103], v122 offset:32816
	v_fmac_f32_e32 v130, v170, v32
	v_fmac_f32_e32 v131, v170, v36
	v_fmac_f32_e32 v132, v170, v40
	v_fmac_f32_e32 v133, v170, v44
	v_fmac_f32_e32 v134, v170, v48
	v_fmac_f32_e32 v135, v170, v52
	v_fmac_f32_e32 v136, v170, v56
	v_fmac_f32_e32 v137, v170, v60
	v_mul_f32_e32 v104, v170, v64
	v_add_f32_e32 v127, v127, v104
	v_fmac_f32_e32 v130, v171, v33
	v_fmac_f32_e32 v131, v171, v37
	v_fmac_f32_e32 v132, v171, v41
	v_fmac_f32_e32 v133, v171, v45
	v_fmac_f32_e32 v134, v171, v49
	v_fmac_f32_e32 v135, v171, v53
	v_fmac_f32_e32 v136, v171, v57
	v_fmac_f32_e32 v137, v171, v61
	v_mul_f32_e32 v104, v171, v65
	v_add_f32_e32 v127, v127, v104
	v_fmac_f32_e32 v130, v172, v34
	v_fmac_f32_e32 v131, v172, v38
	v_fmac_f32_e32 v132, v172, v42
	v_fmac_f32_e32 v133, v172, v46
	v_fmac_f32_e32 v134, v172, v50
	v_fmac_f32_e32 v135, v172, v54
	v_fmac_f32_e32 v136, v172, v58
	v_fmac_f32_e32 v137, v172, v62
	v_mul_f32_e32 v104, v172, v66
	v_add_f32_e32 v127, v127, v104
	v_fmac_f32_e32 v130, v173, v35
	v_fmac_f32_e32 v131, v173, v39
	v_fmac_f32_e32 v132, v173, v43
	v_fmac_f32_e32 v133, v173, v47
	v_fmac_f32_e32 v134, v173, v51
	v_fmac_f32_e32 v135, v173, v55
	v_fmac_f32_e32 v136, v173, v59
	v_fmac_f32_e32 v137, v173, v63
	v_mul_f32_e32 v104, v173, v67
	v_add_f32_e32 v127, v127, v104
	s_waitcnt lgkmcnt(0)
	v_fmac_f32_e32 v130, v174, v68
	v_fmac_f32_e32 v131, v174, v72
	v_fmac_f32_e32 v132, v174, v76
	v_fmac_f32_e32 v133, v174, v80
	v_fmac_f32_e32 v134, v174, v84
	v_fmac_f32_e32 v135, v174, v88
	v_fmac_f32_e32 v136, v174, v92
	v_fmac_f32_e32 v137, v174, v96
	v_mul_f32_e32 v104, v174, v100
	v_add_f32_e32 v127, v127, v104
	v_fmac_f32_e32 v130, v175, v69
	v_fmac_f32_e32 v131, v175, v73
	v_fmac_f32_e32 v132, v175, v77
	v_fmac_f32_e32 v133, v175, v81
	v_fmac_f32_e32 v134, v175, v85
	v_fmac_f32_e32 v135, v175, v89
	v_fmac_f32_e32 v136, v175, v93
	v_fmac_f32_e32 v137, v175, v97
	v_mul_f32_e32 v104, v175, v101
	v_add_f32_e32 v127, v127, v104
	v_fmac_f32_e32 v130, v176, v70
	v_fmac_f32_e32 v131, v176, v74
	v_fmac_f32_e32 v132, v176, v78
	v_fmac_f32_e32 v133, v176, v82
	v_fmac_f32_e32 v134, v176, v86
	v_fmac_f32_e32 v135, v176, v90
	v_fmac_f32_e32 v136, v176, v94
	v_fmac_f32_e32 v137, v176, v98
	v_mul_f32_e32 v104, v176, v102
	v_add_f32_e32 v127, v127, v104
	v_fmac_f32_e32 v130, v177, v71
	v_fmac_f32_e32 v131, v177, v75
	v_fmac_f32_e32 v132, v177, v79
	v_fmac_f32_e32 v133, v177, v83
	v_fmac_f32_e32 v134, v177, v87
	v_fmac_f32_e32 v135, v177, v91
	v_fmac_f32_e32 v136, v177, v95
	v_fmac_f32_e32 v137, v177, v99
	v_mul_f32_e32 v104, v177, v103
	v_add_f32_e32 v127, v127, v104
	v_add_u32_e32 v122, 64, v122
	ds_write2st64_b32 v144, v130, v131 offset0:144 offset1:145
	ds_write2st64_b32 v144, v132, v133 offset0:146 offset1:147
	ds_write2st64_b32 v144, v134, v135 offset0:148 offset1:149
	ds_write2st64_b32 v144, v136, v137 offset0:150 offset1:151
	ds_write_b32 v144, v127 offset:38912
	s_waitcnt lgkmcnt(0)
	s_barrier
	s_and_saveexec_b64 s[16:17], s[6:7]
	s_cbranch_execz .LBB0_5
	s_mul_i32 s18, s20, 0x1800
	s_add_i32 s21, s18, s40
	v_or_b32_e32 v0, s21, v118
	v_ashrrev_i32_e32 v1, 31, v0
	s_mul_hi_i32 s19, s20, 9
	s_mul_i32 s18, s20, 9
	v_lshl_add_u64 v[0:1], v[0:1], 2, s[34:35]
	v_lshl_add_u64 v[2:3], s[40:41], 2, v[124:125]
	s_mov_b64 s[20:21], 0
	v_mov_b32_e32 v4, v116
